# GEMM loops: first iteration of each unit peeled with SrcC=0 on the first MFMA of every accumulator (no zero-init), first-segment LDS reads issued at the unit-loop head
# baseline (speedup 1.0000x reference)
.LBB0_435:
	s_add_i32 s22, 0, 0x10000
	s_add_i32 s23, 0, 0x14000
	v_add_u32_e32 v134, s22, v191
	v_add_u32_e32 v182, s23, v191
	ds_read_b128 v[114:117], v134
	ds_read_b128 v[126:129], v134 offset:1024
	ds_read_b128 v[130:133], v134 offset:2048
	ds_read_b128 v[134:137], v134 offset:3072
	ds_read_b128 v[146:149], v182
	ds_read_b128 v[150:153], v182 offset:1024
	ds_read_b128 v[158:161], v182 offset:2048
	ds_read_b128 v[182:185], v182 offset:3072
	ds_read_b128 v[186:189], v193
	ds_read_b128 v[194:197], v193 offset:1024
	ds_read_b128 v[198:201], v193 offset:2048
	ds_read_b128 v[214:217], v193 offset:3072
	ds_read_b128 v[218:221], v193 offset:4096
	ds_read_b128 v[222:225], v193 offset:5120
	ds_read_b128 v[226:229], v193 offset:6144
	ds_read_b128 v[230:233], v193 offset:7168
	s_add_i32 s79, s79, 1
	s_mul_i32 s20, s79, s67
	s_mul_hi_u32 s21, s79, s66
	s_add_i32 s21, s21, s20
	s_mul_i32 s20, s79, s66
	v_readlane_b32 s12, v247, 0
	v_readlane_b32 s13, v247, 1
	s_add_u32 s48, s20, s12
	s_addc_u32 s49, s21, s13
	v_cmp_gt_i64_e32 vcc, s[48:49], v[168:169]
	v_cmp_lt_i64_e64 s[56:57], s[48:49], v[170:171]
	s_cbranch_vccnz .LBB0_441
	s_ashr_i32 s20, s48, 31
	s_lshr_b32 s20, s20, 29
	s_add_i32 s20, s48, s20
	s_and_b32 s21, s20, -8
	s_sub_i32 s21, s48, s21
	s_cmp_gt_i32 s21, -1
	s_mov_b64 s[48:49], -1
	s_cbranch_scc0 .LBB0_438
	s_lshl_b32 s50, s21, 6
	s_mov_b64 s[48:49], 0

.LBB0_445:
	s_add_u32 s56, s62, 0xb0080
	s_addc_u32 s57, s63, 0
	s_add_u32 s62, s60, 0x100
	v_mov_b32_e32 v2, 0
	s_addc_u32 s63, s61, 0
	s_mov_b32 s84, -2
	s_waitcnt lgkmcnt(0)
	s_mov_b64 s[12:13], 0xb0000
	s_mov_b64 s[86:87], 0x108000
	s_mov_b64 s[96:97], 0x58080
	s_mov_b64 vcc, 0xb0080
	s_mov_b64 s[0:1], 0x108080
	s_branch .Lmid1_446
.Lmid1_446:
	s_add_i32 s22, 0, 0x10000
	s_add_i32 s23, 0, 0x14000
	s_add_u32 s20, s56, 0xfff50080
	s_addc_u32 s21, s57, -1
	s_cmp_eq_u32 s84, 40
	s_cselect_b32 s61, s49, s21
	s_cselect_b32 s60, s48, s20
	s_cselect_b32 s21, s51, s63
	s_cselect_b32 s20, s50, s62
	v_lshl_add_u64 v[162:163], s[56:57], 0, v[156:157]
	s_add_i32 m0, s47, 0xc000
	s_nop 0
	global_load_lds_dwordx4 v[162:163], off
	v_lshl_add_u64 v[162:163], v[162:163], 0, s[2:3]
	s_add_i32 m0, s47, 0xe000
	s_nop 0
	global_load_lds_dwordx4 v[162:163], off
	s_waitcnt vmcnt(8)
	s_waitcnt lgkmcnt(0)
	s_barrier
	s_setprio 1
	s_waitcnt lgkmcnt(0)
	v_mfma_f32_16x16x32_bf16 v[142:145], v[114:117], v[186:189], 0
	v_mfma_f32_16x16x32_bf16 v[142:145], v[126:129], v[194:197], v[142:145]
	v_mfma_f32_16x16x32_bf16 v[138:141], v[130:133], v[186:189], 0
	v_mfma_f32_16x16x32_bf16 v[138:141], v[134:137], v[194:197], v[138:141]
	v_mfma_f32_16x16x32_bf16 v[110:113], v[114:117], v[198:201], 0
	v_mfma_f32_16x16x32_bf16 v[110:113], v[126:129], v[214:217], v[110:113]
	v_mfma_f32_16x16x32_bf16 v[106:109], v[130:133], v[198:201], 0
	v_mfma_f32_16x16x32_bf16 v[106:109], v[134:137], v[214:217], v[106:109]
	v_mfma_f32_16x16x32_bf16 v[94:97], v[114:117], v[218:221], 0
	v_mfma_f32_16x16x32_bf16 v[94:97], v[126:129], v[222:225], v[94:97]
	v_mfma_f32_16x16x32_bf16 v[90:93], v[130:133], v[218:221], 0
	v_mfma_f32_16x16x32_bf16 v[90:93], v[134:137], v[222:225], v[90:93]
	v_mfma_f32_16x16x32_bf16 v[78:81], v[114:117], v[226:229], 0
	v_mfma_f32_16x16x32_bf16 v[78:81], v[126:129], v[230:233], v[78:81]
	v_mfma_f32_16x16x32_bf16 v[74:77], v[130:133], v[226:229], 0
	v_mfma_f32_16x16x32_bf16 v[74:77], v[134:137], v[230:233], v[74:77]
	s_setprio 0
	s_setprio 1
	v_mfma_f32_16x16x32_bf16 v[122:125], v[146:149], v[186:189], 0
	v_mfma_f32_16x16x32_bf16 v[122:125], v[150:153], v[194:197], v[122:125]
	v_mfma_f32_16x16x32_bf16 v[118:121], v[158:161], v[186:189], 0
	v_mfma_f32_16x16x32_bf16 v[118:121], v[182:185], v[194:197], v[118:121]
	v_mfma_f32_16x16x32_bf16 v[102:105], v[146:149], v[198:201], 0
	v_mfma_f32_16x16x32_bf16 v[102:105], v[150:153], v[214:217], v[102:105]
	v_mfma_f32_16x16x32_bf16 v[98:101], v[158:161], v[198:201], 0
	v_mfma_f32_16x16x32_bf16 v[98:101], v[182:185], v[214:217], v[98:101]
	v_mfma_f32_16x16x32_bf16 v[86:89], v[146:149], v[218:221], 0
	v_mfma_f32_16x16x32_bf16 v[86:89], v[150:153], v[222:225], v[86:89]
	v_mfma_f32_16x16x32_bf16 v[82:85], v[158:161], v[218:221], 0
	v_mfma_f32_16x16x32_bf16 v[82:85], v[182:185], v[222:225], v[82:85]
	v_mfma_f32_16x16x32_bf16 v[70:73], v[146:149], v[226:229], 0
	v_mfma_f32_16x16x32_bf16 v[70:73], v[150:153], v[230:233], v[70:73]
	v_mfma_f32_16x16x32_bf16 v[66:69], v[158:161], v[226:229], 0
	v_mfma_f32_16x16x32_bf16 v[66:69], v[182:185], v[230:233], v[66:69]
	s_setprio 0
	s_barrier
	ds_read_b128 v[186:189], v193 offset:16384
	ds_read_b128 v[194:197], v193 offset:17408
	ds_read_b128 v[198:201], v193 offset:18432
	ds_read_b128 v[214:217], v193 offset:19456
	ds_read_b128 v[218:221], v193 offset:20480
	ds_read_b128 v[222:225], v193 offset:21504
	ds_read_b128 v[226:229], v193 offset:22528
	ds_read_b128 v[230:233], v193 offset:23552
	v_lshl_add_u64 v[162:163], s[20:21], 0, v[0:1]
	s_add_i32 s20, s22, s46
	s_mov_b32 m0, s20
	s_nop 0
	global_load_lds_dwordx4 v[162:163], off
	v_lshl_add_u64 v[202:203], v[162:163], 0, s[2:3]
	s_add_i32 m0, s20, 0x2000
	s_add_i32 s20, s23, s46
	global_load_lds_dwordx4 v[202:203], off
	v_lshl_add_u64 v[202:203], v[162:163], 0, s[12:13]
	s_mov_b32 m0, s20
	s_nop 0
	global_load_lds_dwordx4 v[202:203], off
	v_lshl_add_u64 v[202:203], v[162:163], 0, s[86:87]
	s_add_i32 m0, s20, 0x2000
	s_nop 0
	global_load_lds_dwordx4 v[202:203], off
	v_lshl_add_u64 v[202:203], s[60:61], 0, v[154:155]
	s_mov_b32 m0, s47
	v_lshl_add_u64 v[234:235], v[202:203], 0, s[2:3]
	global_load_lds_dwordx4 v[202:203], off
	s_mov_b32 m0, s68
	s_nop 0
	global_load_lds_dwordx4 v[234:235], off
	s_waitcnt vmcnt(8)
	s_waitcnt lgkmcnt(0)
	s_barrier
	s_setprio 1
	s_waitcnt lgkmcnt(0)
	v_mfma_f32_16x16x32_bf16 v[62:65], v[114:117], v[186:189], 0
	v_mfma_f32_16x16x32_bf16 v[62:65], v[126:129], v[194:197], v[62:65]
	v_mfma_f32_16x16x32_bf16 v[58:61], v[130:133], v[186:189], 0
	v_mfma_f32_16x16x32_bf16 v[58:61], v[134:137], v[194:197], v[58:61]
	v_mfma_f32_16x16x32_bf16 v[46:49], v[114:117], v[198:201], 0
	v_mfma_f32_16x16x32_bf16 v[46:49], v[126:129], v[214:217], v[46:49]
	v_mfma_f32_16x16x32_bf16 v[42:45], v[130:133], v[198:201], 0
	v_mfma_f32_16x16x32_bf16 v[42:45], v[134:137], v[214:217], v[42:45]
	v_mfma_f32_16x16x32_bf16 v[30:33], v[114:117], v[218:221], 0
	v_mfma_f32_16x16x32_bf16 v[30:33], v[126:129], v[222:225], v[30:33]
	v_mfma_f32_16x16x32_bf16 v[26:29], v[130:133], v[218:221], 0
	v_mfma_f32_16x16x32_bf16 v[26:29], v[134:137], v[222:225], v[26:29]
	v_mfma_f32_16x16x32_bf16 v[14:17], v[114:117], v[226:229], 0
	v_mfma_f32_16x16x32_bf16 v[14:17], v[126:129], v[230:233], v[14:17]
	v_mfma_f32_16x16x32_bf16 v[10:13], v[130:133], v[226:229], 0
	v_mfma_f32_16x16x32_bf16 v[10:13], v[134:137], v[230:233], v[10:13]
	s_setprio 0
	s_setprio 1
	v_mfma_f32_16x16x32_bf16 v[54:57], v[146:149], v[186:189], 0
	v_mfma_f32_16x16x32_bf16 v[54:57], v[150:153], v[194:197], v[54:57]
	v_mfma_f32_16x16x32_bf16 v[50:53], v[158:161], v[186:189], 0
	v_mfma_f32_16x16x32_bf16 v[50:53], v[182:185], v[194:197], v[50:53]
	v_mfma_f32_16x16x32_bf16 v[38:41], v[146:149], v[198:201], 0
	v_mfma_f32_16x16x32_bf16 v[38:41], v[150:153], v[214:217], v[38:41]
	v_mfma_f32_16x16x32_bf16 v[34:37], v[158:161], v[198:201], 0
	v_mfma_f32_16x16x32_bf16 v[34:37], v[182:185], v[214:217], v[34:37]
	v_mfma_f32_16x16x32_bf16 v[22:25], v[146:149], v[218:221], 0
	v_mfma_f32_16x16x32_bf16 v[22:25], v[150:153], v[222:225], v[22:25]
	v_mfma_f32_16x16x32_bf16 v[18:21], v[158:161], v[218:221], 0
	v_mfma_f32_16x16x32_bf16 v[18:21], v[182:185], v[222:225], v[18:21]
	v_mfma_f32_16x16x32_bf16 v[6:9], v[146:149], v[226:229], 0
	v_mfma_f32_16x16x32_bf16 v[6:9], v[150:153], v[230:233], v[6:9]
	v_mfma_f32_16x16x32_bf16 v[2:5], v[158:161], v[226:229], 0
	v_mfma_f32_16x16x32_bf16 v[2:5], v[182:185], v[230:233], v[2:5]
	s_setprio 0
	s_barrier
	s_add_i32 s20, 0, 0x18000
	s_add_i32 s21, 0, 0x1c000
	v_add_u32_e32 v134, s20, v191
	v_add_u32_e32 v182, s21, v191
	ds_read_b128 v[114:117], v134
	ds_read_b128 v[126:129], v134 offset:1024
	ds_read_b128 v[130:133], v134 offset:2048
	ds_read_b128 v[134:137], v134 offset:3072
	ds_read_b128 v[146:149], v182
	ds_read_b128 v[150:153], v182 offset:1024
	ds_read_b128 v[158:161], v182 offset:2048
	ds_read_b128 v[182:185], v182 offset:3072
	ds_read_b128 v[186:189], v193 offset:32768
	ds_read_b128 v[194:197], v193 offset:33792
	ds_read_b128 v[198:201], v193 offset:34816
	ds_read_b128 v[214:217], v193 offset:35840
	ds_read_b128 v[218:221], v193 offset:36864
	ds_read_b128 v[222:225], v193 offset:37888
	ds_read_b128 v[226:229], v193 offset:38912
	ds_read_b128 v[230:233], v193 offset:39936
	s_mov_b32 m0, s69
	v_lshl_add_u64 v[234:235], v[202:203], 0, s[12:13]
	global_load_lds_dwordx4 v[234:235], off
	v_lshl_add_u64 v[234:235], v[202:203], 0, s[86:87]
	s_mov_b32 m0, s76
	s_nop 0
	global_load_lds_dwordx4 v[234:235], off
	s_waitcnt vmcnt(8)
	s_waitcnt lgkmcnt(0)
	s_barrier
	s_setprio 1
	s_waitcnt lgkmcnt(0)
	v_mfma_f32_16x16x32_bf16 v[142:145], v[114:117], v[186:189], v[142:145]
	v_mfma_f32_16x16x32_bf16 v[142:145], v[126:129], v[194:197], v[142:145]
	v_mfma_f32_16x16x32_bf16 v[138:141], v[130:133], v[186:189], v[138:141]
	v_mfma_f32_16x16x32_bf16 v[138:141], v[134:137], v[194:197], v[138:141]
	v_mfma_f32_16x16x32_bf16 v[110:113], v[114:117], v[198:201], v[110:113]
	v_mfma_f32_16x16x32_bf16 v[110:113], v[126:129], v[214:217], v[110:113]
	v_mfma_f32_16x16x32_bf16 v[106:109], v[130:133], v[198:201], v[106:109]
	v_mfma_f32_16x16x32_bf16 v[106:109], v[134:137], v[214:217], v[106:109]
	v_mfma_f32_16x16x32_bf16 v[94:97], v[114:117], v[218:221], v[94:97]
	v_mfma_f32_16x16x32_bf16 v[94:97], v[126:129], v[222:225], v[94:97]
	v_mfma_f32_16x16x32_bf16 v[90:93], v[130:133], v[218:221], v[90:93]
	v_mfma_f32_16x16x32_bf16 v[90:93], v[134:137], v[222:225], v[90:93]
	v_mfma_f32_16x16x32_bf16 v[78:81], v[114:117], v[226:229], v[78:81]
	v_mfma_f32_16x16x32_bf16 v[78:81], v[126:129], v[230:233], v[78:81]
	v_mfma_f32_16x16x32_bf16 v[74:77], v[130:133], v[226:229], v[74:77]
	v_mfma_f32_16x16x32_bf16 v[74:77], v[134:137], v[230:233], v[74:77]
	s_setprio 0
	s_setprio 1
	v_mfma_f32_16x16x32_bf16 v[122:125], v[146:149], v[186:189], v[122:125]
	v_mfma_f32_16x16x32_bf16 v[122:125], v[150:153], v[194:197], v[122:125]
	v_mfma_f32_16x16x32_bf16 v[118:121], v[158:161], v[186:189], v[118:121]
	v_mfma_f32_16x16x32_bf16 v[118:121], v[182:185], v[194:197], v[118:121]
	v_mfma_f32_16x16x32_bf16 v[102:105], v[146:149], v[198:201], v[102:105]
	v_mfma_f32_16x16x32_bf16 v[102:105], v[150:153], v[214:217], v[102:105]
	v_mfma_f32_16x16x32_bf16 v[98:101], v[158:161], v[198:201], v[98:101]
	v_mfma_f32_16x16x32_bf16 v[98:101], v[182:185], v[214:217], v[98:101]
	v_mfma_f32_16x16x32_bf16 v[86:89], v[146:149], v[218:221], v[86:89]
	v_mfma_f32_16x16x32_bf16 v[86:89], v[150:153], v[222:225], v[86:89]
	v_mfma_f32_16x16x32_bf16 v[82:85], v[158:161], v[218:221], v[82:85]
	v_mfma_f32_16x16x32_bf16 v[82:85], v[182:185], v[222:225], v[82:85]
	v_mfma_f32_16x16x32_bf16 v[70:73], v[146:149], v[226:229], v[70:73]
	v_mfma_f32_16x16x32_bf16 v[70:73], v[150:153], v[230:233], v[70:73]
	v_mfma_f32_16x16x32_bf16 v[66:69], v[158:161], v[226:229], v[66:69]
	v_mfma_f32_16x16x32_bf16 v[66:69], v[182:185], v[230:233], v[66:69]
	s_setprio 0
	s_barrier
	ds_read_b128 v[186:189], v193 offset:49152
	ds_read_b128 v[194:197], v193 offset:50176
	ds_read_b128 v[198:201], v193 offset:51200
	ds_read_b128 v[214:217], v193 offset:52224
	ds_read_b128 v[218:221], v193 offset:53248
	ds_read_b128 v[222:225], v193 offset:54272
	ds_read_b128 v[226:229], v193 offset:55296
	ds_read_b128 v[230:233], v193 offset:56320
	s_add_i32 s20, s20, s46
	v_lshl_add_u64 v[234:235], v[162:163], 0, s[34:35]
	s_mov_b32 m0, s20
	s_nop 0
	global_load_lds_dwordx4 v[234:235], off
	v_lshl_add_u64 v[234:235], v[162:163], 0, s[96:97]
	s_add_i32 m0, s20, 0x2000
	s_add_i32 s20, s21, s46
	global_load_lds_dwordx4 v[234:235], off
	v_lshl_add_u64 v[234:235], v[162:163], 0, vcc
	s_mov_b32 m0, s20
	v_lshl_add_u64 v[162:163], v[162:163], 0, s[0:1]
	global_load_lds_dwordx4 v[234:235], off
	s_add_i32 m0, s20, 0x2000
	s_nop 0
	global_load_lds_dwordx4 v[162:163], off
	v_lshl_add_u64 v[162:163], v[202:203], 0, s[34:35]
	s_mov_b32 m0, s77
	s_nop 0
	global_load_lds_dwordx4 v[162:163], off
	v_lshl_add_u64 v[162:163], v[202:203], 0, s[96:97]
	s_mov_b32 m0, s78
	s_nop 0
	global_load_lds_dwordx4 v[162:163], off
	s_waitcnt vmcnt(8)
	s_waitcnt lgkmcnt(0)
	s_barrier
	s_setprio 1
	s_waitcnt lgkmcnt(0)
	v_mfma_f32_16x16x32_bf16 v[62:65], v[114:117], v[186:189], v[62:65]
	v_mfma_f32_16x16x32_bf16 v[62:65], v[126:129], v[194:197], v[62:65]
	v_mfma_f32_16x16x32_bf16 v[58:61], v[130:133], v[186:189], v[58:61]
	v_mfma_f32_16x16x32_bf16 v[58:61], v[134:137], v[194:197], v[58:61]
	v_mfma_f32_16x16x32_bf16 v[46:49], v[114:117], v[198:201], v[46:49]
	v_mfma_f32_16x16x32_bf16 v[46:49], v[126:129], v[214:217], v[46:49]
	v_mfma_f32_16x16x32_bf16 v[42:45], v[130:133], v[198:201], v[42:45]
	v_mfma_f32_16x16x32_bf16 v[42:45], v[134:137], v[214:217], v[42:45]
	v_mfma_f32_16x16x32_bf16 v[30:33], v[114:117], v[218:221], v[30:33]
	v_mfma_f32_16x16x32_bf16 v[30:33], v[126:129], v[222:225], v[30:33]
	v_mfma_f32_16x16x32_bf16 v[26:29], v[130:133], v[218:221], v[26:29]
	v_mfma_f32_16x16x32_bf16 v[26:29], v[134:137], v[222:225], v[26:29]
	v_mfma_f32_16x16x32_bf16 v[14:17], v[114:117], v[226:229], v[14:17]
	v_mfma_f32_16x16x32_bf16 v[14:17], v[126:129], v[230:233], v[14:17]
	v_mfma_f32_16x16x32_bf16 v[10:13], v[130:133], v[226:229], v[10:13]
	v_mfma_f32_16x16x32_bf16 v[10:13], v[134:137], v[230:233], v[10:13]
	s_add_i32 s84, s84, 2
	s_add_u32 s56, s56, 0x100
	s_addc_u32 s57, s57, 0
	s_add_u32 s62, s62, 0x100
	s_addc_u32 s63, s63, 0
	s_setprio 0
	s_setprio 1
	v_mfma_f32_16x16x32_bf16 v[54:57], v[146:149], v[186:189], v[54:57]
	v_mfma_f32_16x16x32_bf16 v[54:57], v[150:153], v[194:197], v[54:57]
	v_mfma_f32_16x16x32_bf16 v[50:53], v[158:161], v[186:189], v[50:53]
	v_mfma_f32_16x16x32_bf16 v[50:53], v[182:185], v[194:197], v[50:53]
	v_mfma_f32_16x16x32_bf16 v[38:41], v[146:149], v[198:201], v[38:41]
	v_mfma_f32_16x16x32_bf16 v[38:41], v[150:153], v[214:217], v[38:41]
	v_mfma_f32_16x16x32_bf16 v[34:37], v[158:161], v[198:201], v[34:37]
	v_mfma_f32_16x16x32_bf16 v[34:37], v[182:185], v[214:217], v[34:37]
	v_mfma_f32_16x16x32_bf16 v[22:25], v[146:149], v[218:221], v[22:25]
	v_mfma_f32_16x16x32_bf16 v[22:25], v[150:153], v[222:225], v[22:25]
	v_mfma_f32_16x16x32_bf16 v[18:21], v[158:161], v[218:221], v[18:21]
	v_mfma_f32_16x16x32_bf16 v[18:21], v[182:185], v[222:225], v[18:21]
	v_mfma_f32_16x16x32_bf16 v[6:9], v[146:149], v[226:229], v[6:9]
	v_mfma_f32_16x16x32_bf16 v[6:9], v[150:153], v[230:233], v[6:9]
	v_mfma_f32_16x16x32_bf16 v[2:5], v[158:161], v[226:229], v[2:5]
	v_mfma_f32_16x16x32_bf16 v[2:5], v[182:185], v[230:233], v[2:5]
	s_setprio 0
	s_barrier
	s_branch .LBB0_446
	.p2alignl 6, 3212836864

.LBB0_485:
	s_add_i32 s22, 0, 0x10000
	v_add_u32_e32 v152, s22, v139
	s_add_i32 s23, 0, 0x14000
	ds_read_b128 v[134:137], v152
	ds_read_b128 v[144:147], v152 offset:1024
	ds_read_b128 v[148:151], v152 offset:2048
	ds_read_b128 v[152:155], v152 offset:3072
	v_add_u32_e32 v186, s23, v139
	ds_read_b128 v[156:159], v186
	ds_read_b128 v[160:163], v186 offset:1024
	ds_read_b128 v[182:185], v186 offset:2048
	ds_read_b128 v[186:189], v186 offset:3072
	ds_read_b128 v[190:193], v142
	ds_read_b128 v[194:197], v142 offset:1024
	ds_read_b128 v[198:201], v142 offset:2048
	ds_read_b128 v[214:217], v142 offset:3072
	ds_read_b128 v[218:221], v142 offset:4096
	ds_read_b128 v[222:225], v142 offset:5120
	ds_read_b128 v[226:229], v142 offset:6144
	ds_read_b128 v[230:233], v142 offset:7168
	s_add_i32 s89, s85, 1
	s_mul_i32 s20, s89, s67
	s_mul_hi_u32 s21, s89, s66
	s_add_i32 s21, s21, s20
	s_mul_i32 s20, s89, s66
	v_readlane_b32 s12, v247, 0
	v_readlane_b32 s13, v247, 1
	s_add_u32 s60, s20, s12
	s_addc_u32 s61, s21, s13
	v_cmp_gt_i64_e32 vcc, s[60:61], v[164:165]
	v_cmp_lt_i64_e64 s[54:55], s[60:61], v[174:175]
	s_cbranch_vccnz .LBB0_487
	s_ashr_i32 s20, s60, 31
	s_lshr_b32 s20, s20, 29
	s_add_i32 s20, s60, s20
	s_ashr_i32 s21, s20, 3
	s_and_b32 s20, s20, -8
	s_sub_i32 s20, s60, s20
	s_cmp_lt_i32 s20, 0
	s_movk_i32 s12, 0x161
	s_cselect_b32 s22, s12, 0x160
	s_mul_i32 s20, s20, s22
	s_add_i32 s20, s20, s21
	s_mul_hi_i32 s21, s20, 0x2e8ba2e9
	s_lshr_b32 s22, s21, 31
	s_ashr_i32 s21, s21, 4
	s_add_i32 s21, s21, s22
	s_lshl_b32 s22, s21, 2
	s_sub_i32 s23, 0x80, s22
	s_min_i32 s23, s23, 4
	s_abs_i32 s50, s23
	v_cvt_f32_u32_e32 v2, s50
	s_sub_i32 s56, 0, s50
	s_mulk_i32 s21, 0x58
	s_sub_i32 s20, s20, s21
	v_rcp_iflag_f32_e32 v2, v2
	s_abs_i32 s21, s20
	s_xor_b32 s51, s20, s23
	s_ashr_i32 s51, s51, 31
	v_mul_f32_e32 v2, 0x4f7ffffe, v2
	v_cvt_u32_f32_e32 v2, v2
	s_nop 0
	v_readfirstlane_b32 s57, v2
	s_mul_i32 s56, s56, s57
	s_mul_hi_u32 s56, s57, s56
	s_add_i32 s57, s57, s56
	s_mul_hi_u32 s56, s21, s57
	s_mul_i32 s57, s56, s50
	s_sub_i32 s21, s21, s57
	s_add_i32 s60, s56, 1
	s_sub_i32 s57, s21, s50
	s_cmp_ge_u32 s21, s50
	s_cselect_b32 s56, s60, s56
	s_cselect_b32 s21, s57, s21
	s_add_i32 s57, s56, 1
	s_cmp_ge_u32 s21, s50
	s_cselect_b32 s21, s57, s56
	s_xor_b32 s21, s21, s51
	s_sub_i32 s50, s21, s51
	s_mul_i32 s21, s50, s23
	s_sub_i32 s20, s20, s21
	s_add_i32 s56, s22, s20
.LBB0_487:
	s_ashr_i32 s57, s56, 31
	s_lshl_b64 s[20:21], s[56:57], 19
	s_add_u32 s60, s94, s20
	s_addc_u32 s61, s95, s21
	s_and_b64 s[20:21], s[54:55], exec
	s_cselect_b32 s57, s61, s69
	s_cselect_b32 s86, s60, s68
	s_ashr_i32 s51, s50, 31
	s_lshl_b64 s[20:21], s[50:51], 19
	s_add_u32 s62, s15, s20
	s_addc_u32 s63, s42, s21
	s_and_b64 s[20:21], s[54:55], exec
	s_cselect_b32 s51, s63, s77
	s_cselect_b32 s87, s62, s76
	s_add_u32 s68, s68, 0x40080
	s_addc_u32 s69, s69, 0
	s_add_u32 s91, s76, 0x100
	v_mov_b32_e32 v2, 0
	s_addc_u32 s96, s77, 0
	s_mov_b32 s97, -2
	s_branch .Lmid1_488
.Lmid1_488:
	s_add_i32 s22, 0, 0x10000
	s_add_i32 s23, 0, 0x14000
	s_add_u32 s20, s68, 0xfffc0080
	s_addc_u32 s21, s69, -1
	s_cmp_eq_u32 s97, 12
	s_cselect_b32 s77, s57, s21
	s_cselect_b32 s76, s86, s20
	s_cselect_b32 s21, s51, s96
	s_cselect_b32 s20, s87, s91
	v_lshl_add_u64 v[202:203], s[68:69], 0, v[132:133]
	s_add_i32 m0, s43, 0xc000
	s_nop 0
	global_load_lds_dwordx4 v[202:203], off
	v_lshl_add_u64 v[202:203], v[202:203], 0, s[72:73]
	s_add_i32 m0, s43, 0xe000
	s_nop 0
	global_load_lds_dwordx4 v[202:203], off
	s_waitcnt vmcnt(8)
	s_waitcnt lgkmcnt(0)
	s_barrier
	s_setprio 1
	s_waitcnt lgkmcnt(0)
	v_mfma_f32_16x16x32_bf16 v[126:129], v[134:137], v[190:193], 0
	v_mfma_f32_16x16x32_bf16 v[126:129], v[144:147], v[194:197], v[126:129]
	v_mfma_f32_16x16x32_bf16 v[114:117], v[148:151], v[190:193], 0
	v_mfma_f32_16x16x32_bf16 v[114:117], v[152:155], v[194:197], v[114:117]
	v_mfma_f32_16x16x32_bf16 v[110:113], v[134:137], v[198:201], 0
	v_mfma_f32_16x16x32_bf16 v[110:113], v[144:147], v[214:217], v[110:113]
	v_mfma_f32_16x16x32_bf16 v[98:101], v[148:151], v[198:201], 0
	v_mfma_f32_16x16x32_bf16 v[98:101], v[152:155], v[214:217], v[98:101]
	v_mfma_f32_16x16x32_bf16 v[94:97], v[134:137], v[218:221], 0
	v_mfma_f32_16x16x32_bf16 v[94:97], v[144:147], v[222:225], v[94:97]
	v_mfma_f32_16x16x32_bf16 v[82:85], v[148:151], v[218:221], 0
	v_mfma_f32_16x16x32_bf16 v[82:85], v[152:155], v[222:225], v[82:85]
	v_mfma_f32_16x16x32_bf16 v[78:81], v[134:137], v[226:229], 0
	v_mfma_f32_16x16x32_bf16 v[78:81], v[144:147], v[230:233], v[78:81]
	v_mfma_f32_16x16x32_bf16 v[66:69], v[148:151], v[226:229], 0
	v_mfma_f32_16x16x32_bf16 v[66:69], v[152:155], v[230:233], v[66:69]
	s_setprio 0
	s_setprio 1
	v_mfma_f32_16x16x32_bf16 v[122:125], v[156:159], v[190:193], 0
	v_mfma_f32_16x16x32_bf16 v[122:125], v[160:163], v[194:197], v[122:125]
	v_mfma_f32_16x16x32_bf16 v[118:121], v[182:185], v[190:193], 0
	v_mfma_f32_16x16x32_bf16 v[118:121], v[186:189], v[194:197], v[118:121]
	v_mfma_f32_16x16x32_bf16 v[106:109], v[156:159], v[198:201], 0
	v_mfma_f32_16x16x32_bf16 v[106:109], v[160:163], v[214:217], v[106:109]
	v_mfma_f32_16x16x32_bf16 v[102:105], v[182:185], v[198:201], 0
	v_mfma_f32_16x16x32_bf16 v[102:105], v[186:189], v[214:217], v[102:105]
	v_mfma_f32_16x16x32_bf16 v[90:93], v[156:159], v[218:221], 0
	v_mfma_f32_16x16x32_bf16 v[90:93], v[160:163], v[222:225], v[90:93]
	v_mfma_f32_16x16x32_bf16 v[86:89], v[182:185], v[218:221], 0
	v_mfma_f32_16x16x32_bf16 v[86:89], v[186:189], v[222:225], v[86:89]
	v_mfma_f32_16x16x32_bf16 v[74:77], v[156:159], v[226:229], 0
	v_mfma_f32_16x16x32_bf16 v[74:77], v[160:163], v[230:233], v[74:77]
	v_mfma_f32_16x16x32_bf16 v[70:73], v[182:185], v[226:229], 0
	v_mfma_f32_16x16x32_bf16 v[70:73], v[186:189], v[230:233], v[70:73]
	s_setprio 0
	s_barrier
	ds_read_b128 v[190:193], v142 offset:16384
	ds_read_b128 v[194:197], v142 offset:17408
	ds_read_b128 v[198:201], v142 offset:18432
	ds_read_b128 v[214:217], v142 offset:19456
	ds_read_b128 v[218:221], v142 offset:20480
	ds_read_b128 v[222:225], v142 offset:21504
	ds_read_b128 v[226:229], v142 offset:22528
	ds_read_b128 v[230:233], v142 offset:23552
	v_lshl_add_u64 v[202:203], s[20:21], 0, v[0:1]
	s_add_i32 s20, s22, s14
	s_mov_b32 m0, s20
	s_nop 0
	global_load_lds_dwordx4 v[202:203], off
	v_lshl_add_u64 v[234:235], v[202:203], 0, s[72:73]
	s_add_i32 m0, s20, 0x2000
	s_add_i32 s20, s23, s14
	global_load_lds_dwordx4 v[234:235], off
	v_lshl_add_u64 v[234:235], v[202:203], 0, s[28:29]
	s_mov_b32 m0, s20
	s_nop 0
	global_load_lds_dwordx4 v[234:235], off
	v_lshl_add_u64 v[234:235], v[202:203], 0, s[82:83]
	s_add_i32 m0, s20, 0x2000
	s_nop 0
	global_load_lds_dwordx4 v[234:235], off
	v_lshl_add_u64 v[234:235], s[76:77], 0, v[130:131]
	s_mov_b32 m0, s43
	v_lshl_add_u64 v[236:237], v[234:235], 0, s[72:73]
	global_load_lds_dwordx4 v[234:235], off
	s_mov_b32 m0, s46
	s_nop 0
	global_load_lds_dwordx4 v[236:237], off
	s_waitcnt vmcnt(8)
	s_waitcnt lgkmcnt(0)
	s_barrier
	s_setprio 1
	s_waitcnt lgkmcnt(0)
	v_mfma_f32_16x16x32_bf16 v[62:65], v[134:137], v[190:193], 0
	v_mfma_f32_16x16x32_bf16 v[62:65], v[144:147], v[194:197], v[62:65]
	v_mfma_f32_16x16x32_bf16 v[50:53], v[148:151], v[190:193], 0
	v_mfma_f32_16x16x32_bf16 v[50:53], v[152:155], v[194:197], v[50:53]
	v_mfma_f32_16x16x32_bf16 v[46:49], v[134:137], v[198:201], 0
	v_mfma_f32_16x16x32_bf16 v[46:49], v[144:147], v[214:217], v[46:49]
	v_mfma_f32_16x16x32_bf16 v[34:37], v[148:151], v[198:201], 0
	v_mfma_f32_16x16x32_bf16 v[34:37], v[152:155], v[214:217], v[34:37]
	v_mfma_f32_16x16x32_bf16 v[30:33], v[134:137], v[218:221], 0
	v_mfma_f32_16x16x32_bf16 v[30:33], v[144:147], v[222:225], v[30:33]
	v_mfma_f32_16x16x32_bf16 v[18:21], v[148:151], v[218:221], 0
	v_mfma_f32_16x16x32_bf16 v[18:21], v[152:155], v[222:225], v[18:21]
	v_mfma_f32_16x16x32_bf16 v[14:17], v[134:137], v[226:229], 0
	v_mfma_f32_16x16x32_bf16 v[14:17], v[144:147], v[230:233], v[14:17]
	v_mfma_f32_16x16x32_bf16 v[6:9], v[148:151], v[226:229], 0
	v_mfma_f32_16x16x32_bf16 v[6:9], v[152:155], v[230:233], v[6:9]
	s_setprio 0
	s_setprio 1
	v_mfma_f32_16x16x32_bf16 v[58:61], v[156:159], v[190:193], 0
	v_mfma_f32_16x16x32_bf16 v[58:61], v[160:163], v[194:197], v[58:61]
	v_mfma_f32_16x16x32_bf16 v[54:57], v[182:185], v[190:193], 0
	v_mfma_f32_16x16x32_bf16 v[54:57], v[186:189], v[194:197], v[54:57]
	v_mfma_f32_16x16x32_bf16 v[42:45], v[156:159], v[198:201], 0
	v_mfma_f32_16x16x32_bf16 v[42:45], v[160:163], v[214:217], v[42:45]
	v_mfma_f32_16x16x32_bf16 v[38:41], v[182:185], v[198:201], 0
	v_mfma_f32_16x16x32_bf16 v[38:41], v[186:189], v[214:217], v[38:41]
	v_mfma_f32_16x16x32_bf16 v[26:29], v[156:159], v[218:221], 0
	v_mfma_f32_16x16x32_bf16 v[26:29], v[160:163], v[222:225], v[26:29]
	v_mfma_f32_16x16x32_bf16 v[22:25], v[182:185], v[218:221], 0
	v_mfma_f32_16x16x32_bf16 v[22:25], v[186:189], v[222:225], v[22:25]
	v_mfma_f32_16x16x32_bf16 v[10:13], v[156:159], v[226:229], 0
	v_mfma_f32_16x16x32_bf16 v[10:13], v[160:163], v[230:233], v[10:13]
	v_mfma_f32_16x16x32_bf16 v[2:5], v[182:185], v[226:229], 0
	v_mfma_f32_16x16x32_bf16 v[2:5], v[186:189], v[230:233], v[2:5]
	s_setprio 0
	s_barrier
	s_add_i32 s20, 0, 0x18000
	v_add_u32_e32 v143, s20, v139
	s_add_i32 s21, 0, 0x1c000
	ds_read_b128 v[134:137], v143
	ds_read_b128 v[144:147], v143 offset:1024
	ds_read_b128 v[148:151], v143 offset:2048
	ds_read_b128 v[152:155], v143 offset:3072
	v_add_u32_e32 v143, s21, v139
	ds_read_b128 v[156:159], v143
	ds_read_b128 v[160:163], v143 offset:1024
	ds_read_b128 v[182:185], v143 offset:2048
	ds_read_b128 v[186:189], v143 offset:3072
	ds_read_b128 v[190:193], v142 offset:32768
	ds_read_b128 v[194:197], v142 offset:33792
	ds_read_b128 v[198:201], v142 offset:34816
	ds_read_b128 v[214:217], v142 offset:35840
	ds_read_b128 v[218:221], v142 offset:36864
	ds_read_b128 v[222:225], v142 offset:37888
	ds_read_b128 v[226:229], v142 offset:38912
	ds_read_b128 v[230:233], v142 offset:39936
	s_mov_b32 m0, s47
	v_lshl_add_u64 v[236:237], v[234:235], 0, s[28:29]
	global_load_lds_dwordx4 v[236:237], off
	v_lshl_add_u64 v[236:237], v[234:235], 0, s[82:83]
	s_mov_b32 m0, s78
	s_nop 0
	global_load_lds_dwordx4 v[236:237], off
	s_waitcnt vmcnt(8)
	s_waitcnt lgkmcnt(0)
	s_barrier
	s_setprio 1
	s_waitcnt lgkmcnt(0)
	v_mfma_f32_16x16x32_bf16 v[126:129], v[134:137], v[190:193], v[126:129]
	v_mfma_f32_16x16x32_bf16 v[126:129], v[144:147], v[194:197], v[126:129]
	v_mfma_f32_16x16x32_bf16 v[114:117], v[148:151], v[190:193], v[114:117]
	v_mfma_f32_16x16x32_bf16 v[114:117], v[152:155], v[194:197], v[114:117]
	v_mfma_f32_16x16x32_bf16 v[110:113], v[134:137], v[198:201], v[110:113]
	v_mfma_f32_16x16x32_bf16 v[110:113], v[144:147], v[214:217], v[110:113]
	v_mfma_f32_16x16x32_bf16 v[98:101], v[148:151], v[198:201], v[98:101]
	v_mfma_f32_16x16x32_bf16 v[98:101], v[152:155], v[214:217], v[98:101]
	v_mfma_f32_16x16x32_bf16 v[94:97], v[134:137], v[218:221], v[94:97]
	v_mfma_f32_16x16x32_bf16 v[94:97], v[144:147], v[222:225], v[94:97]
	v_mfma_f32_16x16x32_bf16 v[82:85], v[148:151], v[218:221], v[82:85]
	v_mfma_f32_16x16x32_bf16 v[82:85], v[152:155], v[222:225], v[82:85]
	v_mfma_f32_16x16x32_bf16 v[78:81], v[134:137], v[226:229], v[78:81]
	v_mfma_f32_16x16x32_bf16 v[78:81], v[144:147], v[230:233], v[78:81]
	v_mfma_f32_16x16x32_bf16 v[66:69], v[148:151], v[226:229], v[66:69]
	v_mfma_f32_16x16x32_bf16 v[66:69], v[152:155], v[230:233], v[66:69]
	s_setprio 0
	s_setprio 1
	v_mfma_f32_16x16x32_bf16 v[122:125], v[156:159], v[190:193], v[122:125]
	v_mfma_f32_16x16x32_bf16 v[122:125], v[160:163], v[194:197], v[122:125]
	v_mfma_f32_16x16x32_bf16 v[118:121], v[182:185], v[190:193], v[118:121]
	v_mfma_f32_16x16x32_bf16 v[118:121], v[186:189], v[194:197], v[118:121]
	v_mfma_f32_16x16x32_bf16 v[106:109], v[156:159], v[198:201], v[106:109]
	v_mfma_f32_16x16x32_bf16 v[106:109], v[160:163], v[214:217], v[106:109]
	v_mfma_f32_16x16x32_bf16 v[102:105], v[182:185], v[198:201], v[102:105]
	v_mfma_f32_16x16x32_bf16 v[102:105], v[186:189], v[214:217], v[102:105]
	v_mfma_f32_16x16x32_bf16 v[90:93], v[156:159], v[218:221], v[90:93]
	v_mfma_f32_16x16x32_bf16 v[90:93], v[160:163], v[222:225], v[90:93]
	v_mfma_f32_16x16x32_bf16 v[86:89], v[182:185], v[218:221], v[86:89]
	v_mfma_f32_16x16x32_bf16 v[86:89], v[186:189], v[222:225], v[86:89]
	v_mfma_f32_16x16x32_bf16 v[74:77], v[156:159], v[226:229], v[74:77]
	v_mfma_f32_16x16x32_bf16 v[74:77], v[160:163], v[230:233], v[74:77]
	v_mfma_f32_16x16x32_bf16 v[70:73], v[182:185], v[226:229], v[70:73]
	v_mfma_f32_16x16x32_bf16 v[70:73], v[186:189], v[230:233], v[70:73]
	s_setprio 0
	s_barrier
	ds_read_b128 v[190:193], v142 offset:49152
	ds_read_b128 v[194:197], v142 offset:50176
	ds_read_b128 v[198:201], v142 offset:51200
	ds_read_b128 v[214:217], v142 offset:52224
	ds_read_b128 v[218:221], v142 offset:53248
	ds_read_b128 v[222:225], v142 offset:54272
	ds_read_b128 v[226:229], v142 offset:55296
	ds_read_b128 v[230:233], v142 offset:56320
	s_add_i32 s20, s20, s14
	v_lshl_add_u64 v[236:237], v[202:203], 0, s[34:35]
	s_mov_b32 m0, s20
	s_nop 0
	global_load_lds_dwordx4 v[236:237], off
	v_lshl_add_u64 v[236:237], v[202:203], 0, s[38:39]
	s_add_i32 m0, s20, 0x2000
	s_add_i32 s20, s21, s14
	global_load_lds_dwordx4 v[236:237], off
	v_lshl_add_u64 v[236:237], v[202:203], 0, s[44:45]
	s_mov_b32 m0, s20
	v_lshl_add_u64 v[202:203], v[202:203], 0, s[10:11]
	global_load_lds_dwordx4 v[236:237], off
	s_add_i32 m0, s20, 0x2000
	s_nop 0
	global_load_lds_dwordx4 v[202:203], off
	v_lshl_add_u64 v[202:203], v[234:235], 0, s[34:35]
	s_mov_b32 m0, s79
	s_nop 0
	global_load_lds_dwordx4 v[202:203], off
	v_lshl_add_u64 v[202:203], v[234:235], 0, s[38:39]
	s_mov_b32 m0, s88
	s_nop 0
	global_load_lds_dwordx4 v[202:203], off
	s_waitcnt vmcnt(8)
	s_waitcnt lgkmcnt(0)
	s_barrier
	s_setprio 1
	s_waitcnt lgkmcnt(0)
	v_mfma_f32_16x16x32_bf16 v[62:65], v[134:137], v[190:193], v[62:65]
	v_mfma_f32_16x16x32_bf16 v[62:65], v[144:147], v[194:197], v[62:65]
	v_mfma_f32_16x16x32_bf16 v[50:53], v[148:151], v[190:193], v[50:53]
	v_mfma_f32_16x16x32_bf16 v[50:53], v[152:155], v[194:197], v[50:53]
	v_mfma_f32_16x16x32_bf16 v[46:49], v[134:137], v[198:201], v[46:49]
	v_mfma_f32_16x16x32_bf16 v[46:49], v[144:147], v[214:217], v[46:49]
	v_mfma_f32_16x16x32_bf16 v[34:37], v[148:151], v[198:201], v[34:37]
	v_mfma_f32_16x16x32_bf16 v[34:37], v[152:155], v[214:217], v[34:37]
	v_mfma_f32_16x16x32_bf16 v[30:33], v[134:137], v[218:221], v[30:33]
	v_mfma_f32_16x16x32_bf16 v[30:33], v[144:147], v[222:225], v[30:33]
	v_mfma_f32_16x16x32_bf16 v[18:21], v[148:151], v[218:221], v[18:21]
	v_mfma_f32_16x16x32_bf16 v[18:21], v[152:155], v[222:225], v[18:21]
	v_mfma_f32_16x16x32_bf16 v[14:17], v[134:137], v[226:229], v[14:17]
	v_mfma_f32_16x16x32_bf16 v[14:17], v[144:147], v[230:233], v[14:17]
	v_mfma_f32_16x16x32_bf16 v[6:9], v[148:151], v[226:229], v[6:9]
	v_mfma_f32_16x16x32_bf16 v[6:9], v[152:155], v[230:233], v[6:9]
	s_add_i32 s97, s97, 2
	s_add_u32 s68, s68, 0x100
	s_addc_u32 s69, s69, 0
	s_add_u32 s91, s91, 0x100
	s_addc_u32 s96, s96, 0
	s_setprio 0
	s_setprio 1
	v_mfma_f32_16x16x32_bf16 v[58:61], v[156:159], v[190:193], v[58:61]
	v_mfma_f32_16x16x32_bf16 v[58:61], v[160:163], v[194:197], v[58:61]
	v_mfma_f32_16x16x32_bf16 v[54:57], v[182:185], v[190:193], v[54:57]
	v_mfma_f32_16x16x32_bf16 v[54:57], v[186:189], v[194:197], v[54:57]
	v_mfma_f32_16x16x32_bf16 v[42:45], v[156:159], v[198:201], v[42:45]
	v_mfma_f32_16x16x32_bf16 v[42:45], v[160:163], v[214:217], v[42:45]
	v_mfma_f32_16x16x32_bf16 v[38:41], v[182:185], v[198:201], v[38:41]
	v_mfma_f32_16x16x32_bf16 v[38:41], v[186:189], v[214:217], v[38:41]
	v_mfma_f32_16x16x32_bf16 v[26:29], v[156:159], v[218:221], v[26:29]
	v_mfma_f32_16x16x32_bf16 v[26:29], v[160:163], v[222:225], v[26:29]
	v_mfma_f32_16x16x32_bf16 v[22:25], v[182:185], v[218:221], v[22:25]
	v_mfma_f32_16x16x32_bf16 v[22:25], v[186:189], v[222:225], v[22:25]
	v_mfma_f32_16x16x32_bf16 v[10:13], v[156:159], v[226:229], v[10:13]
	v_mfma_f32_16x16x32_bf16 v[10:13], v[160:163], v[230:233], v[10:13]
	v_mfma_f32_16x16x32_bf16 v[2:5], v[182:185], v[226:229], v[2:5]
	v_mfma_f32_16x16x32_bf16 v[2:5], v[186:189], v[230:233], v[2:5]
	s_setprio 0
	s_barrier
	s_branch .LBB0_488
	.p2alignl 6, 3212836864

.LBB0_597:
	s_add_i32 s22, 0, 0x10000
	s_add_i32 s23, 0, 0x14000
	v_add_u32_e32 v150, s22, v139
	v_add_u32_e32 v186, s23, v139
	ds_read_b128 v[134:137], v150
	ds_read_b128 v[142:145], v150 offset:1024
	ds_read_b128 v[146:149], v150 offset:2048
	ds_read_b128 v[150:153], v150 offset:3072
	ds_read_b128 v[154:157], v186
	ds_read_b128 v[158:161], v186 offset:1024
	ds_read_b128 v[182:185], v186 offset:2048
	ds_read_b128 v[186:189], v186 offset:3072
	ds_read_b128 v[190:193], v141
	ds_read_b128 v[194:197], v141 offset:1024
	ds_read_b128 v[198:201], v141 offset:2048
	ds_read_b128 v[214:217], v141 offset:3072
	ds_read_b128 v[218:221], v141 offset:4096
	ds_read_b128 v[222:225], v141 offset:5120
	ds_read_b128 v[226:229], v141 offset:6144
	ds_read_b128 v[230:233], v141 offset:7168
	s_add_i32 s59, s59, 1
	s_mul_i32 s20, s59, s67
	s_mul_hi_u32 s21, s59, s66
	s_add_i32 s21, s21, s20
	s_mul_i32 s20, s59, s66
	v_readlane_b32 s12, v247, 0
	v_readlane_b32 s13, v247, 1
	s_add_u32 s40, s20, s12
	s_addc_u32 s41, s21, s13
	v_cmp_gt_i64_e32 vcc, s[40:41], v[178:179]
	v_cmp_lt_i64_e64 s[56:57], s[40:41], v[176:177]
	s_cbranch_vccnz .LBB0_603
	s_ashr_i32 s20, s40, 31
	s_lshr_b32 s20, s20, 29
	s_add_i32 s20, s40, s20
	s_and_b32 s21, s20, -8
	s_sub_i32 s21, s40, s21
	s_cmp_gt_i32 s21, -1
	s_mov_b64 s[40:41], -1
	s_cbranch_scc0 .LBB0_600
	s_lshl_b32 s42, s21, 5
	s_mov_b64 s[40:41], 0

.LBB0_603:
	s_ashr_i32 s51, s50, 31
	s_lshl_b64 s[20:21], s[50:51], 18
	s_add_u32 s78, s0, s20
	s_addc_u32 s79, s1, s21
	s_and_b64 s[20:21], s[56:57], exec
	s_cselect_b32 s42, s79, s7
	s_cselect_b32 s43, s78, s6
	s_ashr_i32 s49, s48, 31
	s_lshl_b64 s[20:21], s[48:49], 18
	s_add_u32 s40, s76, s20
	s_addc_u32 s41, s77, s21
	s_and_b64 s[20:21], s[56:57], exec
	s_cselect_b32 s46, s41, s69
	s_cselect_b32 s47, s40, s68
	s_add_u32 s6, s6, 0x20080
	s_addc_u32 s7, s7, 0
	s_add_u32 s49, s68, 0x100
	v_mov_b32_e32 v2, 0
	s_addc_u32 s51, s69, 0
	s_mov_b32 s84, -2
	s_waitcnt lgkmcnt(0)
	s_branch .Lmid1_604
.Lmid1_604:
	s_add_i32 s22, 0, 0x10000
	s_add_i32 s23, 0, 0x14000
	s_add_u32 s20, s6, 0xfffe0080
	s_addc_u32 s21, s7, -1
	s_cmp_eq_u32 s84, 4
	s_cselect_b32 s69, s42, s21
	s_cselect_b32 s68, s43, s20
	s_cselect_b32 s21, s46, s51
	s_cselect_b32 s20, s47, s49
	v_lshl_add_u64 v[162:163], s[6:7], 0, v[132:133]
	s_add_i32 m0, s89, 0xc000
	s_nop 0
	global_load_lds_dwordx4 v[162:163], off
	v_lshl_add_u64 v[162:163], v[162:163], 0, s[64:65]
	s_add_i32 m0, s89, 0xe000
	s_nop 0
	global_load_lds_dwordx4 v[162:163], off
	s_waitcnt vmcnt(8)
	s_waitcnt lgkmcnt(0)
	s_barrier
	s_setprio 1
	s_waitcnt lgkmcnt(0)
	v_mfma_f32_16x16x32_bf16 v[126:129], v[134:137], v[190:193], 0
	v_mfma_f32_16x16x32_bf16 v[126:129], v[142:145], v[194:197], v[126:129]
	v_mfma_f32_16x16x32_bf16 v[122:125], v[146:149], v[190:193], 0
	v_mfma_f32_16x16x32_bf16 v[122:125], v[150:153], v[194:197], v[122:125]
	v_mfma_f32_16x16x32_bf16 v[110:113], v[134:137], v[198:201], 0
	v_mfma_f32_16x16x32_bf16 v[110:113], v[142:145], v[214:217], v[110:113]
	v_mfma_f32_16x16x32_bf16 v[106:109], v[146:149], v[198:201], 0
	v_mfma_f32_16x16x32_bf16 v[106:109], v[150:153], v[214:217], v[106:109]
	v_mfma_f32_16x16x32_bf16 v[94:97], v[134:137], v[218:221], 0
	v_mfma_f32_16x16x32_bf16 v[94:97], v[142:145], v[222:225], v[94:97]
	v_mfma_f32_16x16x32_bf16 v[90:93], v[146:149], v[218:221], 0
	v_mfma_f32_16x16x32_bf16 v[90:93], v[150:153], v[222:225], v[90:93]
	v_mfma_f32_16x16x32_bf16 v[78:81], v[134:137], v[226:229], 0
	v_mfma_f32_16x16x32_bf16 v[78:81], v[142:145], v[230:233], v[78:81]
	v_mfma_f32_16x16x32_bf16 v[74:77], v[146:149], v[226:229], 0
	v_mfma_f32_16x16x32_bf16 v[74:77], v[150:153], v[230:233], v[74:77]
	s_setprio 0
	s_setprio 1
	v_mfma_f32_16x16x32_bf16 v[118:121], v[154:157], v[190:193], 0
	v_mfma_f32_16x16x32_bf16 v[118:121], v[158:161], v[194:197], v[118:121]
	v_mfma_f32_16x16x32_bf16 v[114:117], v[182:185], v[190:193], 0
	v_mfma_f32_16x16x32_bf16 v[114:117], v[186:189], v[194:197], v[114:117]
	v_mfma_f32_16x16x32_bf16 v[102:105], v[154:157], v[198:201], 0
	v_mfma_f32_16x16x32_bf16 v[102:105], v[158:161], v[214:217], v[102:105]
	v_mfma_f32_16x16x32_bf16 v[98:101], v[182:185], v[198:201], 0
	v_mfma_f32_16x16x32_bf16 v[98:101], v[186:189], v[214:217], v[98:101]
	v_mfma_f32_16x16x32_bf16 v[86:89], v[154:157], v[218:221], 0
	v_mfma_f32_16x16x32_bf16 v[86:89], v[158:161], v[222:225], v[86:89]
	v_mfma_f32_16x16x32_bf16 v[82:85], v[182:185], v[218:221], 0
	v_mfma_f32_16x16x32_bf16 v[82:85], v[186:189], v[222:225], v[82:85]
	v_mfma_f32_16x16x32_bf16 v[70:73], v[154:157], v[226:229], 0
	v_mfma_f32_16x16x32_bf16 v[70:73], v[158:161], v[230:233], v[70:73]
	v_mfma_f32_16x16x32_bf16 v[66:69], v[182:185], v[226:229], 0
	v_mfma_f32_16x16x32_bf16 v[66:69], v[186:189], v[230:233], v[66:69]
	s_setprio 0
	s_barrier
	ds_read_b128 v[190:193], v141 offset:16384
	ds_read_b128 v[194:197], v141 offset:17408
	ds_read_b128 v[198:201], v141 offset:18432
	ds_read_b128 v[214:217], v141 offset:19456
	ds_read_b128 v[218:221], v141 offset:20480
	ds_read_b128 v[222:225], v141 offset:21504
	ds_read_b128 v[226:229], v141 offset:22528
	ds_read_b128 v[230:233], v141 offset:23552
	v_lshl_add_u64 v[162:163], s[20:21], 0, v[0:1]
	s_add_i32 s20, s22, s88
	s_mov_b32 m0, s20
	s_nop 0
	global_load_lds_dwordx4 v[162:163], off
	v_lshl_add_u64 v[202:203], v[162:163], 0, s[64:65]
	s_add_i32 m0, s20, 0x2000
	s_add_i32 s20, s23, s88
	global_load_lds_dwordx4 v[202:203], off
	v_lshl_add_u64 v[202:203], v[162:163], 0, s[72:73]
	s_mov_b32 m0, s20
	s_nop 0
	global_load_lds_dwordx4 v[202:203], off
	v_lshl_add_u64 v[202:203], v[162:163], 0, s[74:75]
	s_add_i32 m0, s20, 0x2000
	s_nop 0
	global_load_lds_dwordx4 v[202:203], off
	v_lshl_add_u64 v[202:203], s[68:69], 0, v[130:131]
	s_mov_b32 m0, s89
	v_lshl_add_u64 v[234:235], v[202:203], 0, s[64:65]
	global_load_lds_dwordx4 v[202:203], off
	s_mov_b32 m0, s90
	s_nop 0
	global_load_lds_dwordx4 v[234:235], off
	s_waitcnt vmcnt(8)
	s_waitcnt lgkmcnt(0)
	s_barrier
	s_setprio 1
	s_waitcnt lgkmcnt(0)
	v_mfma_f32_16x16x32_bf16 v[62:65], v[134:137], v[190:193], 0
	v_mfma_f32_16x16x32_bf16 v[62:65], v[142:145], v[194:197], v[62:65]
	v_mfma_f32_16x16x32_bf16 v[58:61], v[146:149], v[190:193], 0
	v_mfma_f32_16x16x32_bf16 v[58:61], v[150:153], v[194:197], v[58:61]
	v_mfma_f32_16x16x32_bf16 v[46:49], v[134:137], v[198:201], 0
	v_mfma_f32_16x16x32_bf16 v[46:49], v[142:145], v[214:217], v[46:49]
	v_mfma_f32_16x16x32_bf16 v[42:45], v[146:149], v[198:201], 0
	v_mfma_f32_16x16x32_bf16 v[42:45], v[150:153], v[214:217], v[42:45]
	v_mfma_f32_16x16x32_bf16 v[30:33], v[134:137], v[218:221], 0
	v_mfma_f32_16x16x32_bf16 v[30:33], v[142:145], v[222:225], v[30:33]
	v_mfma_f32_16x16x32_bf16 v[26:29], v[146:149], v[218:221], 0
	v_mfma_f32_16x16x32_bf16 v[26:29], v[150:153], v[222:225], v[26:29]
	v_mfma_f32_16x16x32_bf16 v[14:17], v[134:137], v[226:229], 0
	v_mfma_f32_16x16x32_bf16 v[14:17], v[142:145], v[230:233], v[14:17]
	v_mfma_f32_16x16x32_bf16 v[10:13], v[146:149], v[226:229], 0
	v_mfma_f32_16x16x32_bf16 v[10:13], v[150:153], v[230:233], v[10:13]
	s_setprio 0
	s_setprio 1
	v_mfma_f32_16x16x32_bf16 v[54:57], v[154:157], v[190:193], 0
	v_mfma_f32_16x16x32_bf16 v[54:57], v[158:161], v[194:197], v[54:57]
	v_mfma_f32_16x16x32_bf16 v[50:53], v[182:185], v[190:193], 0
	v_mfma_f32_16x16x32_bf16 v[50:53], v[186:189], v[194:197], v[50:53]
	v_mfma_f32_16x16x32_bf16 v[38:41], v[154:157], v[198:201], 0
	v_mfma_f32_16x16x32_bf16 v[38:41], v[158:161], v[214:217], v[38:41]
	v_mfma_f32_16x16x32_bf16 v[34:37], v[182:185], v[198:201], 0
	v_mfma_f32_16x16x32_bf16 v[34:37], v[186:189], v[214:217], v[34:37]
	v_mfma_f32_16x16x32_bf16 v[22:25], v[154:157], v[218:221], 0
	v_mfma_f32_16x16x32_bf16 v[22:25], v[158:161], v[222:225], v[22:25]
	v_mfma_f32_16x16x32_bf16 v[18:21], v[182:185], v[218:221], 0
	v_mfma_f32_16x16x32_bf16 v[18:21], v[186:189], v[222:225], v[18:21]
	v_mfma_f32_16x16x32_bf16 v[6:9], v[154:157], v[226:229], 0
	v_mfma_f32_16x16x32_bf16 v[6:9], v[158:161], v[230:233], v[6:9]
	v_mfma_f32_16x16x32_bf16 v[2:5], v[182:185], v[226:229], 0
	v_mfma_f32_16x16x32_bf16 v[2:5], v[186:189], v[230:233], v[2:5]
	s_setprio 0
	s_barrier
	s_add_i32 s20, 0, 0x18000
	s_add_i32 s21, 0, 0x1c000
	v_add_u32_e32 v150, s20, v139
	v_add_u32_e32 v186, s21, v139
	ds_read_b128 v[134:137], v150
	ds_read_b128 v[142:145], v150 offset:1024
	ds_read_b128 v[146:149], v150 offset:2048
	ds_read_b128 v[150:153], v150 offset:3072
	ds_read_b128 v[154:157], v186
	ds_read_b128 v[158:161], v186 offset:1024
	ds_read_b128 v[182:185], v186 offset:2048
	ds_read_b128 v[186:189], v186 offset:3072
	ds_read_b128 v[190:193], v141 offset:32768
	ds_read_b128 v[194:197], v141 offset:33792
	ds_read_b128 v[198:201], v141 offset:34816
	ds_read_b128 v[214:217], v141 offset:35840
	ds_read_b128 v[218:221], v141 offset:36864
	ds_read_b128 v[222:225], v141 offset:37888
	ds_read_b128 v[226:229], v141 offset:38912
	ds_read_b128 v[230:233], v141 offset:39936
	s_mov_b32 m0, s91
	v_lshl_add_u64 v[234:235], v[202:203], 0, s[72:73]
	global_load_lds_dwordx4 v[234:235], off
	v_lshl_add_u64 v[234:235], v[202:203], 0, s[74:75]
	s_mov_b32 m0, s96
	s_nop 0
	global_load_lds_dwordx4 v[234:235], off
	s_waitcnt vmcnt(8)
	s_waitcnt lgkmcnt(0)
	s_barrier
	s_setprio 1
	s_waitcnt lgkmcnt(0)
	v_mfma_f32_16x16x32_bf16 v[126:129], v[134:137], v[190:193], v[126:129]
	v_mfma_f32_16x16x32_bf16 v[126:129], v[142:145], v[194:197], v[126:129]
	v_mfma_f32_16x16x32_bf16 v[122:125], v[146:149], v[190:193], v[122:125]
	v_mfma_f32_16x16x32_bf16 v[122:125], v[150:153], v[194:197], v[122:125]
	v_mfma_f32_16x16x32_bf16 v[110:113], v[134:137], v[198:201], v[110:113]
	v_mfma_f32_16x16x32_bf16 v[110:113], v[142:145], v[214:217], v[110:113]
	v_mfma_f32_16x16x32_bf16 v[106:109], v[146:149], v[198:201], v[106:109]
	v_mfma_f32_16x16x32_bf16 v[106:109], v[150:153], v[214:217], v[106:109]
	v_mfma_f32_16x16x32_bf16 v[94:97], v[134:137], v[218:221], v[94:97]
	v_mfma_f32_16x16x32_bf16 v[94:97], v[142:145], v[222:225], v[94:97]
	v_mfma_f32_16x16x32_bf16 v[90:93], v[146:149], v[218:221], v[90:93]
	v_mfma_f32_16x16x32_bf16 v[90:93], v[150:153], v[222:225], v[90:93]
	v_mfma_f32_16x16x32_bf16 v[78:81], v[134:137], v[226:229], v[78:81]
	v_mfma_f32_16x16x32_bf16 v[78:81], v[142:145], v[230:233], v[78:81]
	v_mfma_f32_16x16x32_bf16 v[74:77], v[146:149], v[226:229], v[74:77]
	v_mfma_f32_16x16x32_bf16 v[74:77], v[150:153], v[230:233], v[74:77]
	s_setprio 0
	s_setprio 1
	v_mfma_f32_16x16x32_bf16 v[118:121], v[154:157], v[190:193], v[118:121]
	v_mfma_f32_16x16x32_bf16 v[118:121], v[158:161], v[194:197], v[118:121]
	v_mfma_f32_16x16x32_bf16 v[114:117], v[182:185], v[190:193], v[114:117]
	v_mfma_f32_16x16x32_bf16 v[114:117], v[186:189], v[194:197], v[114:117]
	v_mfma_f32_16x16x32_bf16 v[102:105], v[154:157], v[198:201], v[102:105]
	v_mfma_f32_16x16x32_bf16 v[102:105], v[158:161], v[214:217], v[102:105]
	v_mfma_f32_16x16x32_bf16 v[98:101], v[182:185], v[198:201], v[98:101]
	v_mfma_f32_16x16x32_bf16 v[98:101], v[186:189], v[214:217], v[98:101]
	v_mfma_f32_16x16x32_bf16 v[86:89], v[154:157], v[218:221], v[86:89]
	v_mfma_f32_16x16x32_bf16 v[86:89], v[158:161], v[222:225], v[86:89]
	v_mfma_f32_16x16x32_bf16 v[82:85], v[182:185], v[218:221], v[82:85]
	v_mfma_f32_16x16x32_bf16 v[82:85], v[186:189], v[222:225], v[82:85]
	v_mfma_f32_16x16x32_bf16 v[70:73], v[154:157], v[226:229], v[70:73]
	v_mfma_f32_16x16x32_bf16 v[70:73], v[158:161], v[230:233], v[70:73]
	v_mfma_f32_16x16x32_bf16 v[66:69], v[182:185], v[226:229], v[66:69]
	v_mfma_f32_16x16x32_bf16 v[66:69], v[186:189], v[230:233], v[66:69]
	s_setprio 0
	s_barrier
	ds_read_b128 v[190:193], v141 offset:49152
	ds_read_b128 v[194:197], v141 offset:50176
	ds_read_b128 v[198:201], v141 offset:51200
	ds_read_b128 v[214:217], v141 offset:52224
	ds_read_b128 v[218:221], v141 offset:53248
	ds_read_b128 v[222:225], v141 offset:54272
	ds_read_b128 v[226:229], v141 offset:55296
	ds_read_b128 v[230:233], v141 offset:56320
	s_add_i32 s20, s20, s88
	v_lshl_add_u64 v[234:235], v[162:163], 0, s[34:35]
	s_mov_b32 m0, s20
	s_nop 0
	global_load_lds_dwordx4 v[234:235], off
	v_lshl_add_u64 v[234:235], v[162:163], 0, s[80:81]
	s_add_i32 m0, s20, 0x2000
	s_add_i32 s20, s21, s88
	global_load_lds_dwordx4 v[234:235], off
	v_lshl_add_u64 v[234:235], v[162:163], 0, s[38:39]
	s_mov_b32 m0, s20
	v_lshl_add_u64 v[162:163], v[162:163], 0, s[86:87]
	global_load_lds_dwordx4 v[234:235], off
	s_add_i32 m0, s20, 0x2000
	s_nop 0
	global_load_lds_dwordx4 v[162:163], off
	v_lshl_add_u64 v[162:163], v[202:203], 0, s[34:35]
	s_mov_b32 m0, s97
	s_nop 0
	global_load_lds_dwordx4 v[162:163], off
	v_lshl_add_u64 v[162:163], v[202:203], 0, s[80:81]
	s_mov_b32 m0, s58
	s_nop 0
	global_load_lds_dwordx4 v[162:163], off
	s_waitcnt vmcnt(8)
	s_waitcnt lgkmcnt(0)
	s_barrier
	s_setprio 1
	s_waitcnt lgkmcnt(0)
	v_mfma_f32_16x16x32_bf16 v[62:65], v[134:137], v[190:193], v[62:65]
	v_mfma_f32_16x16x32_bf16 v[62:65], v[142:145], v[194:197], v[62:65]
	v_mfma_f32_16x16x32_bf16 v[58:61], v[146:149], v[190:193], v[58:61]
	v_mfma_f32_16x16x32_bf16 v[58:61], v[150:153], v[194:197], v[58:61]
	v_mfma_f32_16x16x32_bf16 v[46:49], v[134:137], v[198:201], v[46:49]
	v_mfma_f32_16x16x32_bf16 v[46:49], v[142:145], v[214:217], v[46:49]
	v_mfma_f32_16x16x32_bf16 v[42:45], v[146:149], v[198:201], v[42:45]
	v_mfma_f32_16x16x32_bf16 v[42:45], v[150:153], v[214:217], v[42:45]
	v_mfma_f32_16x16x32_bf16 v[30:33], v[134:137], v[218:221], v[30:33]
	v_mfma_f32_16x16x32_bf16 v[30:33], v[142:145], v[222:225], v[30:33]
	v_mfma_f32_16x16x32_bf16 v[26:29], v[146:149], v[218:221], v[26:29]
	v_mfma_f32_16x16x32_bf16 v[26:29], v[150:153], v[222:225], v[26:29]
	v_mfma_f32_16x16x32_bf16 v[14:17], v[134:137], v[226:229], v[14:17]
	v_mfma_f32_16x16x32_bf16 v[14:17], v[142:145], v[230:233], v[14:17]
	v_mfma_f32_16x16x32_bf16 v[10:13], v[146:149], v[226:229], v[10:13]
	v_mfma_f32_16x16x32_bf16 v[10:13], v[150:153], v[230:233], v[10:13]
	s_add_i32 s84, s84, 2
	s_add_u32 s6, s6, 0x100
	s_addc_u32 s7, s7, 0
	s_add_u32 s49, s49, 0x100
	s_addc_u32 s51, s51, 0
	s_setprio 0
	s_setprio 1
	v_mfma_f32_16x16x32_bf16 v[54:57], v[154:157], v[190:193], v[54:57]
	v_mfma_f32_16x16x32_bf16 v[54:57], v[158:161], v[194:197], v[54:57]
	v_mfma_f32_16x16x32_bf16 v[50:53], v[182:185], v[190:193], v[50:53]
	v_mfma_f32_16x16x32_bf16 v[50:53], v[186:189], v[194:197], v[50:53]
	v_mfma_f32_16x16x32_bf16 v[38:41], v[154:157], v[198:201], v[38:41]
	v_mfma_f32_16x16x32_bf16 v[38:41], v[158:161], v[214:217], v[38:41]
	v_mfma_f32_16x16x32_bf16 v[34:37], v[182:185], v[198:201], v[34:37]
	v_mfma_f32_16x16x32_bf16 v[34:37], v[186:189], v[214:217], v[34:37]
	v_mfma_f32_16x16x32_bf16 v[22:25], v[154:157], v[218:221], v[22:25]
	v_mfma_f32_16x16x32_bf16 v[22:25], v[158:161], v[222:225], v[22:25]
	v_mfma_f32_16x16x32_bf16 v[18:21], v[182:185], v[218:221], v[18:21]
	v_mfma_f32_16x16x32_bf16 v[18:21], v[186:189], v[222:225], v[18:21]
	v_mfma_f32_16x16x32_bf16 v[6:9], v[154:157], v[226:229], v[6:9]
	v_mfma_f32_16x16x32_bf16 v[6:9], v[158:161], v[230:233], v[6:9]
	v_mfma_f32_16x16x32_bf16 v[2:5], v[182:185], v[226:229], v[2:5]
	v_mfma_f32_16x16x32_bf16 v[2:5], v[186:189], v[230:233], v[2:5]
	s_setprio 0
	s_barrier
	s_branch .LBB0_604
	.p2alignl 6, 3212836864

.LBB0_771:
	s_add_i32 s22, 0, 0x10000
	s_add_i32 s23, 0, 0x14000
	v_add_u32_e32 v142, s22, v193
	v_add_u32_e32 v158, s23, v193
	ds_read_b128 v[130:133], v142
	ds_read_b128 v[134:137], v142 offset:1024
	ds_read_b128 v[138:141], v142 offset:2048
	ds_read_b128 v[142:145], v142 offset:3072
	ds_read_b128 v[146:149], v158
	ds_read_b128 v[150:153], v158 offset:1024
	ds_read_b128 v[154:157], v158 offset:2048
	ds_read_b128 v[158:161], v158 offset:3072
	ds_read_b128 v[184:187], v196
	ds_read_b128 v[188:191], v196 offset:1024
	ds_read_b128 v[198:201], v196 offset:2048
	ds_read_b128 v[214:217], v196 offset:3072
	ds_read_b128 v[218:221], v196 offset:4096
	ds_read_b128 v[222:225], v196 offset:5120
	ds_read_b128 v[226:229], v196 offset:6144
	ds_read_b128 v[230:233], v196 offset:7168
	s_add_i32 s91, s96, 1
	s_mul_i32 s20, s91, s67
	s_mul_hi_u32 s21, s91, s66
	s_add_i32 s21, s21, s20
	s_mul_i32 s20, s91, s66
	v_readlane_b32 s12, v247, 0
	v_readlane_b32 s13, v247, 1
	s_add_u32 s62, s20, s12
	s_addc_u32 s63, s21, s13
	v_cmp_gt_i64_e32 vcc, s[62:63], v[168:169]
	v_cmp_lt_i64_e64 s[56:57], s[62:63], v[170:171]
	s_cbranch_vccnz .LBB0_777
	s_ashr_i32 s20, s62, 31
	s_lshr_b32 s20, s20, 29
	s_add_i32 s20, s62, s20
	s_and_b32 s21, s20, -8
	s_sub_i32 s21, s62, s21
	s_cmp_gt_i32 s21, -1
	s_mov_b64 s[58:59], -1
	s_cbranch_scc0 .LBB0_774
	s_lshl_b32 s60, s21, 6
	s_mov_b64 s[58:59], 0

.LBB0_777:
	s_ashr_i32 s61, s60, 31
	s_lshl_b64 s[20:21], s[60:61], 19
	s_add_u32 s62, s94, s20
	s_addc_u32 s63, s95, s21
	s_and_b64 s[20:21], s[56:57], exec
	s_cselect_b32 s61, s63, s77
	s_cselect_b32 s85, s62, s76
	s_ashr_i32 s59, s58, 31
	s_lshl_b64 s[20:21], s[58:59], 19
	s_add_u32 s68, s15, s20
	s_addc_u32 s69, s42, s21
	s_and_b64 s[20:21], s[56:57], exec
	s_cselect_b32 s59, s69, s79
	s_cselect_b32 s86, s68, s78
	s_add_u32 s76, s76, 0x40080
	s_addc_u32 s77, s77, 0
	s_add_u32 s87, s78, 0x100
	v_mov_b32_e32 v2, 0
	s_addc_u32 vcc_lo, s79, 0
	s_mov_b32 vcc_hi, -2
	s_waitcnt lgkmcnt(0)
	s_branch .Lmid1_778
.Lmid1_778:
	s_add_i32 s22, 0, 0x10000
	s_add_i32 s23, 0, 0x14000
	s_add_u32 s20, s76, 0xfffc0080
	s_addc_u32 s21, s77, -1
	s_cmp_eq_u32 vcc_hi, 12
	s_cselect_b32 s79, s61, s21
	s_cselect_b32 s78, s85, s20
	s_cselect_b32 s21, s59, vcc_lo
	s_cselect_b32 s20, s86, s87
	v_lshl_add_u64 v[202:203], s[76:77], 0, v[182:183]
	s_add_i32 m0, s43, 0xc000
	s_nop 0
	global_load_lds_dwordx4 v[202:203], off
	v_lshl_add_u64 v[202:203], v[202:203], 0, s[72:73]
	s_add_i32 m0, s43, 0xe000
	s_nop 0
	global_load_lds_dwordx4 v[202:203], off
	s_waitcnt vmcnt(8)
	s_waitcnt lgkmcnt(0)
	s_barrier
	s_setprio 1
	s_waitcnt lgkmcnt(0)
	v_mfma_f32_16x16x32_bf16 v[126:129], v[130:133], v[184:187], 0
	v_mfma_f32_16x16x32_bf16 v[126:129], v[134:137], v[188:191], v[126:129]
	v_mfma_f32_16x16x32_bf16 v[122:125], v[138:141], v[184:187], 0
	v_mfma_f32_16x16x32_bf16 v[122:125], v[142:145], v[188:191], v[122:125]
	v_mfma_f32_16x16x32_bf16 v[110:113], v[130:133], v[198:201], 0
	v_mfma_f32_16x16x32_bf16 v[110:113], v[134:137], v[214:217], v[110:113]
	v_mfma_f32_16x16x32_bf16 v[106:109], v[138:141], v[198:201], 0
	v_mfma_f32_16x16x32_bf16 v[106:109], v[142:145], v[214:217], v[106:109]
	v_mfma_f32_16x16x32_bf16 v[94:97], v[130:133], v[218:221], 0
	v_mfma_f32_16x16x32_bf16 v[94:97], v[134:137], v[222:225], v[94:97]
	v_mfma_f32_16x16x32_bf16 v[90:93], v[138:141], v[218:221], 0
	v_mfma_f32_16x16x32_bf16 v[90:93], v[142:145], v[222:225], v[90:93]
	v_mfma_f32_16x16x32_bf16 v[78:81], v[130:133], v[226:229], 0
	v_mfma_f32_16x16x32_bf16 v[78:81], v[134:137], v[230:233], v[78:81]
	v_mfma_f32_16x16x32_bf16 v[74:77], v[138:141], v[226:229], 0
	v_mfma_f32_16x16x32_bf16 v[74:77], v[142:145], v[230:233], v[74:77]
	s_setprio 0
	s_setprio 1
	v_mfma_f32_16x16x32_bf16 v[118:121], v[146:149], v[184:187], 0
	v_mfma_f32_16x16x32_bf16 v[118:121], v[150:153], v[188:191], v[118:121]
	v_mfma_f32_16x16x32_bf16 v[114:117], v[154:157], v[184:187], 0
	v_mfma_f32_16x16x32_bf16 v[114:117], v[158:161], v[188:191], v[114:117]
	v_mfma_f32_16x16x32_bf16 v[102:105], v[146:149], v[198:201], 0
	v_mfma_f32_16x16x32_bf16 v[102:105], v[150:153], v[214:217], v[102:105]
	v_mfma_f32_16x16x32_bf16 v[98:101], v[154:157], v[198:201], 0
	v_mfma_f32_16x16x32_bf16 v[98:101], v[158:161], v[214:217], v[98:101]
	v_mfma_f32_16x16x32_bf16 v[86:89], v[146:149], v[218:221], 0
	v_mfma_f32_16x16x32_bf16 v[86:89], v[150:153], v[222:225], v[86:89]
	v_mfma_f32_16x16x32_bf16 v[82:85], v[154:157], v[218:221], 0
	v_mfma_f32_16x16x32_bf16 v[82:85], v[158:161], v[222:225], v[82:85]
	v_mfma_f32_16x16x32_bf16 v[70:73], v[146:149], v[226:229], 0
	v_mfma_f32_16x16x32_bf16 v[70:73], v[150:153], v[230:233], v[70:73]
	v_mfma_f32_16x16x32_bf16 v[66:69], v[154:157], v[226:229], 0
	v_mfma_f32_16x16x32_bf16 v[66:69], v[158:161], v[230:233], v[66:69]
	s_setprio 0
	s_barrier
	ds_read_b128 v[184:187], v196 offset:16384
	ds_read_b128 v[188:191], v196 offset:17408
	ds_read_b128 v[198:201], v196 offset:18432
	ds_read_b128 v[214:217], v196 offset:19456
	ds_read_b128 v[218:221], v196 offset:20480
	ds_read_b128 v[222:225], v196 offset:21504
	ds_read_b128 v[226:229], v196 offset:22528
	ds_read_b128 v[230:233], v196 offset:23552
	v_lshl_add_u64 v[202:203], s[20:21], 0, v[0:1]
	s_add_i32 s20, s22, s14
	s_mov_b32 m0, s20
	s_nop 0
	global_load_lds_dwordx4 v[202:203], off
	v_lshl_add_u64 v[234:235], v[202:203], 0, s[72:73]
	s_add_i32 m0, s20, 0x2000
	s_add_i32 s20, s23, s14
	global_load_lds_dwordx4 v[234:235], off
	v_lshl_add_u64 v[234:235], v[202:203], 0, s[28:29]
	s_mov_b32 m0, s20
	s_nop 0
	global_load_lds_dwordx4 v[234:235], off
	v_lshl_add_u64 v[234:235], v[202:203], 0, s[82:83]
	s_add_i32 m0, s20, 0x2000
	s_nop 0
	global_load_lds_dwordx4 v[234:235], off
	v_lshl_add_u64 v[234:235], s[78:79], 0, v[162:163]
	s_mov_b32 m0, s43
	v_lshl_add_u64 v[236:237], v[234:235], 0, s[72:73]
	global_load_lds_dwordx4 v[234:235], off
	s_mov_b32 m0, s46
	s_nop 0
	global_load_lds_dwordx4 v[236:237], off
	s_waitcnt vmcnt(8)
	s_waitcnt lgkmcnt(0)
	s_barrier
	s_setprio 1
	s_waitcnt lgkmcnt(0)
	v_mfma_f32_16x16x32_bf16 v[62:65], v[130:133], v[184:187], 0
	v_mfma_f32_16x16x32_bf16 v[62:65], v[134:137], v[188:191], v[62:65]
	v_mfma_f32_16x16x32_bf16 v[58:61], v[138:141], v[184:187], 0
	v_mfma_f32_16x16x32_bf16 v[58:61], v[142:145], v[188:191], v[58:61]
	v_mfma_f32_16x16x32_bf16 v[46:49], v[130:133], v[198:201], 0
	v_mfma_f32_16x16x32_bf16 v[46:49], v[134:137], v[214:217], v[46:49]
	v_mfma_f32_16x16x32_bf16 v[42:45], v[138:141], v[198:201], 0
	v_mfma_f32_16x16x32_bf16 v[42:45], v[142:145], v[214:217], v[42:45]
	v_mfma_f32_16x16x32_bf16 v[30:33], v[130:133], v[218:221], 0
	v_mfma_f32_16x16x32_bf16 v[30:33], v[134:137], v[222:225], v[30:33]
	v_mfma_f32_16x16x32_bf16 v[26:29], v[138:141], v[218:221], 0
	v_mfma_f32_16x16x32_bf16 v[26:29], v[142:145], v[222:225], v[26:29]
	v_mfma_f32_16x16x32_bf16 v[14:17], v[130:133], v[226:229], 0
	v_mfma_f32_16x16x32_bf16 v[14:17], v[134:137], v[230:233], v[14:17]
	v_mfma_f32_16x16x32_bf16 v[10:13], v[138:141], v[226:229], 0
	v_mfma_f32_16x16x32_bf16 v[10:13], v[142:145], v[230:233], v[10:13]
	s_setprio 0
	s_setprio 1
	v_mfma_f32_16x16x32_bf16 v[54:57], v[146:149], v[184:187], 0
	v_mfma_f32_16x16x32_bf16 v[54:57], v[150:153], v[188:191], v[54:57]
	v_mfma_f32_16x16x32_bf16 v[50:53], v[154:157], v[184:187], 0
	v_mfma_f32_16x16x32_bf16 v[50:53], v[158:161], v[188:191], v[50:53]
	v_mfma_f32_16x16x32_bf16 v[38:41], v[146:149], v[198:201], 0
	v_mfma_f32_16x16x32_bf16 v[38:41], v[150:153], v[214:217], v[38:41]
	v_mfma_f32_16x16x32_bf16 v[34:37], v[154:157], v[198:201], 0
	v_mfma_f32_16x16x32_bf16 v[34:37], v[158:161], v[214:217], v[34:37]
	v_mfma_f32_16x16x32_bf16 v[22:25], v[146:149], v[218:221], 0
	v_mfma_f32_16x16x32_bf16 v[22:25], v[150:153], v[222:225], v[22:25]
	v_mfma_f32_16x16x32_bf16 v[18:21], v[154:157], v[218:221], 0
	v_mfma_f32_16x16x32_bf16 v[18:21], v[158:161], v[222:225], v[18:21]
	v_mfma_f32_16x16x32_bf16 v[6:9], v[146:149], v[226:229], 0
	v_mfma_f32_16x16x32_bf16 v[6:9], v[150:153], v[230:233], v[6:9]
	v_mfma_f32_16x16x32_bf16 v[2:5], v[154:157], v[226:229], 0
	v_mfma_f32_16x16x32_bf16 v[2:5], v[158:161], v[230:233], v[2:5]
	s_setprio 0
	s_barrier
	s_add_i32 s20, 0, 0x18000
	s_add_i32 s21, 0, 0x1c000
	v_add_u32_e32 v142, s20, v193
	v_add_u32_e32 v158, s21, v193
	ds_read_b128 v[130:133], v142
	ds_read_b128 v[134:137], v142 offset:1024
	ds_read_b128 v[138:141], v142 offset:2048
	ds_read_b128 v[142:145], v142 offset:3072
	ds_read_b128 v[146:149], v158
	ds_read_b128 v[150:153], v158 offset:1024
	ds_read_b128 v[154:157], v158 offset:2048
	ds_read_b128 v[158:161], v158 offset:3072
	ds_read_b128 v[184:187], v196 offset:32768
	ds_read_b128 v[188:191], v196 offset:33792
	ds_read_b128 v[198:201], v196 offset:34816
	ds_read_b128 v[214:217], v196 offset:35840
	ds_read_b128 v[218:221], v196 offset:36864
	ds_read_b128 v[222:225], v196 offset:37888
	ds_read_b128 v[226:229], v196 offset:38912
	ds_read_b128 v[230:233], v196 offset:39936
	s_mov_b32 m0, s47
	v_lshl_add_u64 v[236:237], v[234:235], 0, s[28:29]
	global_load_lds_dwordx4 v[236:237], off
	v_lshl_add_u64 v[236:237], v[234:235], 0, s[82:83]
	s_mov_b32 m0, s88
	s_nop 0
	global_load_lds_dwordx4 v[236:237], off
	s_waitcnt vmcnt(8)
	s_waitcnt lgkmcnt(0)
	s_barrier
	s_setprio 1
	s_waitcnt lgkmcnt(0)
	v_mfma_f32_16x16x32_bf16 v[126:129], v[130:133], v[184:187], v[126:129]
	v_mfma_f32_16x16x32_bf16 v[126:129], v[134:137], v[188:191], v[126:129]
	v_mfma_f32_16x16x32_bf16 v[122:125], v[138:141], v[184:187], v[122:125]
	v_mfma_f32_16x16x32_bf16 v[122:125], v[142:145], v[188:191], v[122:125]
	v_mfma_f32_16x16x32_bf16 v[110:113], v[130:133], v[198:201], v[110:113]
	v_mfma_f32_16x16x32_bf16 v[110:113], v[134:137], v[214:217], v[110:113]
	v_mfma_f32_16x16x32_bf16 v[106:109], v[138:141], v[198:201], v[106:109]
	v_mfma_f32_16x16x32_bf16 v[106:109], v[142:145], v[214:217], v[106:109]
	v_mfma_f32_16x16x32_bf16 v[94:97], v[130:133], v[218:221], v[94:97]
	v_mfma_f32_16x16x32_bf16 v[94:97], v[134:137], v[222:225], v[94:97]
	v_mfma_f32_16x16x32_bf16 v[90:93], v[138:141], v[218:221], v[90:93]
	v_mfma_f32_16x16x32_bf16 v[90:93], v[142:145], v[222:225], v[90:93]
	v_mfma_f32_16x16x32_bf16 v[78:81], v[130:133], v[226:229], v[78:81]
	v_mfma_f32_16x16x32_bf16 v[78:81], v[134:137], v[230:233], v[78:81]
	v_mfma_f32_16x16x32_bf16 v[74:77], v[138:141], v[226:229], v[74:77]
	v_mfma_f32_16x16x32_bf16 v[74:77], v[142:145], v[230:233], v[74:77]
	s_setprio 0
	s_setprio 1
	v_mfma_f32_16x16x32_bf16 v[118:121], v[146:149], v[184:187], v[118:121]
	v_mfma_f32_16x16x32_bf16 v[118:121], v[150:153], v[188:191], v[118:121]
	v_mfma_f32_16x16x32_bf16 v[114:117], v[154:157], v[184:187], v[114:117]
	v_mfma_f32_16x16x32_bf16 v[114:117], v[158:161], v[188:191], v[114:117]
	v_mfma_f32_16x16x32_bf16 v[102:105], v[146:149], v[198:201], v[102:105]
	v_mfma_f32_16x16x32_bf16 v[102:105], v[150:153], v[214:217], v[102:105]
	v_mfma_f32_16x16x32_bf16 v[98:101], v[154:157], v[198:201], v[98:101]
	v_mfma_f32_16x16x32_bf16 v[98:101], v[158:161], v[214:217], v[98:101]
	v_mfma_f32_16x16x32_bf16 v[86:89], v[146:149], v[218:221], v[86:89]
	v_mfma_f32_16x16x32_bf16 v[86:89], v[150:153], v[222:225], v[86:89]
	v_mfma_f32_16x16x32_bf16 v[82:85], v[154:157], v[218:221], v[82:85]
	v_mfma_f32_16x16x32_bf16 v[82:85], v[158:161], v[222:225], v[82:85]
	v_mfma_f32_16x16x32_bf16 v[70:73], v[146:149], v[226:229], v[70:73]
	v_mfma_f32_16x16x32_bf16 v[70:73], v[150:153], v[230:233], v[70:73]
	v_mfma_f32_16x16x32_bf16 v[66:69], v[154:157], v[226:229], v[66:69]
	v_mfma_f32_16x16x32_bf16 v[66:69], v[158:161], v[230:233], v[66:69]
	s_setprio 0
	s_barrier
	ds_read_b128 v[184:187], v196 offset:49152
	ds_read_b128 v[188:191], v196 offset:50176
	ds_read_b128 v[198:201], v196 offset:51200
	ds_read_b128 v[214:217], v196 offset:52224
	ds_read_b128 v[218:221], v196 offset:53248
	ds_read_b128 v[222:225], v196 offset:54272
	ds_read_b128 v[226:229], v196 offset:55296
	ds_read_b128 v[230:233], v196 offset:56320
	s_add_i32 s20, s20, s14
	v_lshl_add_u64 v[236:237], v[202:203], 0, s[34:35]
	s_mov_b32 m0, s20
	s_nop 0
	global_load_lds_dwordx4 v[236:237], off
	v_lshl_add_u64 v[236:237], v[202:203], 0, s[38:39]
	s_add_i32 m0, s20, 0x2000
	s_add_i32 s20, s21, s14
	global_load_lds_dwordx4 v[236:237], off
	v_lshl_add_u64 v[236:237], v[202:203], 0, s[44:45]
	s_mov_b32 m0, s20
	v_lshl_add_u64 v[202:203], v[202:203], 0, s[10:11]
	global_load_lds_dwordx4 v[236:237], off
	s_add_i32 m0, s20, 0x2000
	s_nop 0
	global_load_lds_dwordx4 v[202:203], off
	v_lshl_add_u64 v[202:203], v[234:235], 0, s[34:35]
	s_mov_b32 m0, s89
	s_nop 0
	global_load_lds_dwordx4 v[202:203], off
	v_lshl_add_u64 v[202:203], v[234:235], 0, s[38:39]
	s_mov_b32 m0, s90
	s_nop 0
	global_load_lds_dwordx4 v[202:203], off
	s_waitcnt vmcnt(8)
	s_waitcnt lgkmcnt(0)
	s_barrier
	s_setprio 1
	s_waitcnt lgkmcnt(0)
	v_mfma_f32_16x16x32_bf16 v[62:65], v[130:133], v[184:187], v[62:65]
	v_mfma_f32_16x16x32_bf16 v[62:65], v[134:137], v[188:191], v[62:65]
	v_mfma_f32_16x16x32_bf16 v[58:61], v[138:141], v[184:187], v[58:61]
	v_mfma_f32_16x16x32_bf16 v[58:61], v[142:145], v[188:191], v[58:61]
	v_mfma_f32_16x16x32_bf16 v[46:49], v[130:133], v[198:201], v[46:49]
	v_mfma_f32_16x16x32_bf16 v[46:49], v[134:137], v[214:217], v[46:49]
	v_mfma_f32_16x16x32_bf16 v[42:45], v[138:141], v[198:201], v[42:45]
	v_mfma_f32_16x16x32_bf16 v[42:45], v[142:145], v[214:217], v[42:45]
	v_mfma_f32_16x16x32_bf16 v[30:33], v[130:133], v[218:221], v[30:33]
	v_mfma_f32_16x16x32_bf16 v[30:33], v[134:137], v[222:225], v[30:33]
	v_mfma_f32_16x16x32_bf16 v[26:29], v[138:141], v[218:221], v[26:29]
	v_mfma_f32_16x16x32_bf16 v[26:29], v[142:145], v[222:225], v[26:29]
	v_mfma_f32_16x16x32_bf16 v[14:17], v[130:133], v[226:229], v[14:17]
	v_mfma_f32_16x16x32_bf16 v[14:17], v[134:137], v[230:233], v[14:17]
	v_mfma_f32_16x16x32_bf16 v[10:13], v[138:141], v[226:229], v[10:13]
	v_mfma_f32_16x16x32_bf16 v[10:13], v[142:145], v[230:233], v[10:13]
	s_add_i32 vcc_hi, vcc_hi, 2
	s_add_u32 s76, s76, 0x100
	s_addc_u32 s77, s77, 0
	s_add_u32 s87, s87, 0x100
	s_addc_u32 vcc_lo, vcc_lo, 0
	s_setprio 0
	s_setprio 1
	v_mfma_f32_16x16x32_bf16 v[54:57], v[146:149], v[184:187], v[54:57]
	v_mfma_f32_16x16x32_bf16 v[54:57], v[150:153], v[188:191], v[54:57]
	v_mfma_f32_16x16x32_bf16 v[50:53], v[154:157], v[184:187], v[50:53]
	v_mfma_f32_16x16x32_bf16 v[50:53], v[158:161], v[188:191], v[50:53]
	v_mfma_f32_16x16x32_bf16 v[38:41], v[146:149], v[198:201], v[38:41]
	v_mfma_f32_16x16x32_bf16 v[38:41], v[150:153], v[214:217], v[38:41]
	v_mfma_f32_16x16x32_bf16 v[34:37], v[154:157], v[198:201], v[34:37]
	v_mfma_f32_16x16x32_bf16 v[34:37], v[158:161], v[214:217], v[34:37]
	v_mfma_f32_16x16x32_bf16 v[22:25], v[146:149], v[218:221], v[22:25]
	v_mfma_f32_16x16x32_bf16 v[22:25], v[150:153], v[222:225], v[22:25]
	v_mfma_f32_16x16x32_bf16 v[18:21], v[154:157], v[218:221], v[18:21]
	v_mfma_f32_16x16x32_bf16 v[18:21], v[158:161], v[222:225], v[18:21]
	v_mfma_f32_16x16x32_bf16 v[6:9], v[146:149], v[226:229], v[6:9]
	v_mfma_f32_16x16x32_bf16 v[6:9], v[150:153], v[230:233], v[6:9]
	v_mfma_f32_16x16x32_bf16 v[2:5], v[154:157], v[226:229], v[2:5]
	v_mfma_f32_16x16x32_bf16 v[2:5], v[158:161], v[230:233], v[2:5]
	s_setprio 0
	s_barrier
	s_branch .LBB0_778
	.p2alignl 6, 3212836864

.LBB0_847:
	s_add_i32 vcc_lo, 0, 0x10000
	v_add_u32_e32 v158, vcc_lo, v145
	s_add_i32 vcc_hi, 0, 0x14000
	ds_read_b128 v[138:141], v158
	ds_read_b128 v[146:149], v158 offset:1024
	ds_read_b128 v[150:153], v158 offset:2048
	ds_read_b128 v[158:161], v158 offset:3072
	v_add_u32_e32 v194, vcc_hi, v145
	ds_read_b128 v[182:185], v194
	ds_read_b128 v[186:189], v194 offset:1024
	ds_read_b128 v[190:193], v194 offset:2048
	ds_read_b128 v[194:197], v194 offset:3072
	ds_read_b128 v[198:201], v157
	ds_read_b128 v[214:217], v157 offset:1024
	ds_read_b128 v[218:221], v157 offset:2048
	ds_read_b128 v[222:225], v157 offset:3072
	ds_read_b128 v[226:229], v157 offset:4096
	ds_read_b128 v[230:233], v157 offset:5120
	ds_read_b128 v[234:237], v157 offset:6144
	ds_read_b128 v[238:241], v157 offset:7168
	s_add_i32 s97, s85, 1
	s_mul_i32 s20, s97, s67
	s_mul_hi_u32 s21, s97, s66
	s_add_i32 s21, s21, s20
	s_mul_i32 s20, s97, s66
	v_readlane_b32 s12, v247, 0
	v_readlane_b32 s13, v247, 1
	s_add_u32 s76, s20, s12
	s_addc_u32 s77, s21, s13
	v_cmp_gt_i64_e32 vcc, s[76:77], v[166:167]
	v_cmp_lt_i64_e64 s[54:55], s[76:77], v[180:181]
	s_cbranch_vccnz .LBB0_849
	s_ashr_i32 s20, s76, 31
	s_lshr_b32 s20, s20, 29
	s_add_i32 s20, s76, s20
	s_ashr_i32 s21, s20, 3
	s_and_b32 s20, s20, -8
	s_sub_i32 s20, s76, s20
	s_cmp_lt_i32 s20, 0
	s_movk_i32 s12, 0x51
	s_cselect_b32 s68, s12, 0x50
	s_mul_i32 s20, s20, s68
	s_add_i32 s20, s20, s21
	s_mul_hi_i32 s21, s20, 0x66666667
	s_lshr_b32 s68, s21, 31
	s_ashr_i32 s21, s21, 3
	s_add_i32 s21, s21, s68
	s_lshl_b32 s69, s21, 2
	s_sub_i32 s68, 0x80, s69
	s_min_i32 s76, s68, 4
	s_abs_i32 s68, s76
	v_cvt_f32_u32_e32 v0, s68
	s_sub_i32 s78, 0, s68
	s_mul_i32 s21, s21, 20
	s_sub_i32 s20, s20, s21
	v_rcp_iflag_f32_e32 v0, v0
	s_abs_i32 s21, s20
	s_xor_b32 s77, s20, s76
	s_ashr_i32 s77, s77, 31
	v_mul_f32_e32 v0, 0x4f7ffffe, v0
	v_cvt_u32_f32_e32 v0, v0
	s_nop 0
	v_readfirstlane_b32 s79, v0
	s_mul_i32 s78, s78, s79
	s_mul_hi_u32 s78, s79, s78
	s_add_i32 s79, s79, s78
	s_mul_hi_u32 s78, s21, s79
	s_mul_i32 s79, s78, s68
	s_sub_i32 s21, s21, s79
	s_add_i32 s86, s78, 1
	s_sub_i32 s79, s21, s68
	s_cmp_ge_u32 s21, s68
	s_cselect_b32 s78, s86, s78
	s_cselect_b32 s21, s79, s21
	s_add_i32 s79, s78, 1
	s_cmp_ge_u32 s21, s68
	s_cselect_b32 s21, s79, s78
	s_xor_b32 s21, s21, s77
	s_sub_i32 s68, s21, s77
	s_mul_i32 s21, s68, s76
	s_sub_i32 s20, s20, s21
	s_add_i32 s78, s69, s20
.LBB0_849:
	s_ashr_i32 s79, s78, 31
	s_lshl_b64 s[20:21], s[78:79], 19
	s_add_u32 s88, s4, s20
	s_addc_u32 s89, s5, s21
	s_and_b64 s[20:21], s[54:55], exec
	s_cselect_b32 s76, s89, s57
	s_cselect_b32 s77, s88, s56
	s_ashr_i32 s69, s68, 31
	s_lshl_b64 s[20:21], s[68:69], 19
	v_readlane_b32 s12, v247, 42
	s_add_u32 s94, s12, s20
	v_readlane_b32 s12, v245, 61
	s_addc_u32 s95, s12, s21
	s_and_b64 s[20:21], s[54:55], exec
	s_cselect_b32 s69, s95, s59
	s_cselect_b32 s79, s94, s58
	s_add_u32 s56, s56, 0x40080
	s_addc_u32 s57, s57, 0
	s_add_u32 s86, s58, 0x100
	v_mov_b32_e32 v2, 0
	s_addc_u32 s87, s59, 0
	s_mov_b32 s91, -2
	s_branch .Lmid1_850
.Lmid1_850:
	s_add_i32 vcc_lo, 0, 0x10000
	s_add_i32 vcc_hi, 0, 0x14000
	s_add_u32 s20, s56, 0xfffc0080
	s_addc_u32 s21, s57, -1
	s_cmp_eq_u32 s91, 12
	s_cselect_b32 s59, s76, s21
	s_cselect_b32 s58, s77, s20
	s_cselect_b32 s21, s69, s87
	s_cselect_b32 s20, s79, s86
	v_lshl_add_u64 v[142:143], s[56:57], 0, v[136:137]
	s_add_i32 m0, s15, 0xc000
	s_nop 0
	global_load_lds_dwordx4 v[142:143], off
	v_lshl_add_u64 v[142:143], v[142:143], 0, s[72:73]
	s_add_i32 m0, s15, 0xe000
	s_nop 0
	global_load_lds_dwordx4 v[142:143], off
	s_waitcnt vmcnt(8)
	s_waitcnt lgkmcnt(0)
	s_barrier
	s_setprio 1
	s_waitcnt lgkmcnt(0)
	v_mfma_f32_16x16x32_bf16 v[126:129], v[138:141], v[198:201], 0
	v_mfma_f32_16x16x32_bf16 v[126:129], v[146:149], v[214:217], v[126:129]
	v_mfma_f32_16x16x32_bf16 v[122:125], v[150:153], v[198:201], 0
	v_mfma_f32_16x16x32_bf16 v[122:125], v[158:161], v[214:217], v[122:125]
	v_mfma_f32_16x16x32_bf16 v[110:113], v[138:141], v[218:221], 0
	v_mfma_f32_16x16x32_bf16 v[110:113], v[146:149], v[222:225], v[110:113]
	v_mfma_f32_16x16x32_bf16 v[106:109], v[150:153], v[218:221], 0
	v_mfma_f32_16x16x32_bf16 v[106:109], v[158:161], v[222:225], v[106:109]
	v_mfma_f32_16x16x32_bf16 v[94:97], v[138:141], v[226:229], 0
	v_mfma_f32_16x16x32_bf16 v[94:97], v[146:149], v[230:233], v[94:97]
	v_mfma_f32_16x16x32_bf16 v[90:93], v[150:153], v[226:229], 0
	v_mfma_f32_16x16x32_bf16 v[90:93], v[158:161], v[230:233], v[90:93]
	v_mfma_f32_16x16x32_bf16 v[78:81], v[138:141], v[234:237], 0
	v_mfma_f32_16x16x32_bf16 v[78:81], v[146:149], v[238:241], v[78:81]
	v_mfma_f32_16x16x32_bf16 v[74:77], v[150:153], v[234:237], 0
	v_mfma_f32_16x16x32_bf16 v[74:77], v[158:161], v[238:241], v[74:77]
	s_setprio 0
	s_setprio 1
	v_mfma_f32_16x16x32_bf16 v[118:121], v[182:185], v[198:201], 0
	v_mfma_f32_16x16x32_bf16 v[118:121], v[186:189], v[214:217], v[118:121]
	v_mfma_f32_16x16x32_bf16 v[114:117], v[190:193], v[198:201], 0
	v_mfma_f32_16x16x32_bf16 v[114:117], v[194:197], v[214:217], v[114:117]
	v_mfma_f32_16x16x32_bf16 v[102:105], v[182:185], v[218:221], 0
	v_mfma_f32_16x16x32_bf16 v[102:105], v[186:189], v[222:225], v[102:105]
	v_mfma_f32_16x16x32_bf16 v[98:101], v[190:193], v[218:221], 0
	v_mfma_f32_16x16x32_bf16 v[98:101], v[194:197], v[222:225], v[98:101]
	v_mfma_f32_16x16x32_bf16 v[86:89], v[182:185], v[226:229], 0
	v_mfma_f32_16x16x32_bf16 v[86:89], v[186:189], v[230:233], v[86:89]
	v_mfma_f32_16x16x32_bf16 v[82:85], v[190:193], v[226:229], 0
	v_mfma_f32_16x16x32_bf16 v[82:85], v[194:197], v[230:233], v[82:85]
	v_mfma_f32_16x16x32_bf16 v[70:73], v[182:185], v[234:237], 0
	v_mfma_f32_16x16x32_bf16 v[70:73], v[186:189], v[238:241], v[70:73]
	v_mfma_f32_16x16x32_bf16 v[66:69], v[190:193], v[234:237], 0
	v_mfma_f32_16x16x32_bf16 v[66:69], v[194:197], v[238:241], v[66:69]
	s_setprio 0
	s_barrier
	ds_read_b128 v[198:201], v157 offset:16384
	ds_read_b128 v[214:217], v157 offset:17408
	ds_read_b128 v[218:221], v157 offset:18432
	ds_read_b128 v[222:225], v157 offset:19456
	ds_read_b128 v[226:229], v157 offset:20480
	ds_read_b128 v[230:233], v157 offset:21504
	ds_read_b128 v[234:237], v157 offset:22528
	ds_read_b128 v[238:241], v157 offset:23552
	v_lshl_add_u64 v[142:143], s[20:21], 0, v[130:131]
	s_add_i32 s20, vcc_lo, s14
	s_mov_b32 m0, s20
	s_nop 0
	global_load_lds_dwordx4 v[142:143], off
	v_lshl_add_u64 v[162:163], v[142:143], 0, s[72:73]
	s_add_i32 m0, s20, 0x2000
	s_add_i32 s20, vcc_hi, s14
	global_load_lds_dwordx4 v[162:163], off
	v_lshl_add_u64 v[162:163], v[142:143], 0, s[28:29]
	s_mov_b32 m0, s20
	s_nop 0
	global_load_lds_dwordx4 v[162:163], off
	v_lshl_add_u64 v[162:163], v[142:143], 0, s[82:83]
	s_add_i32 m0, s20, 0x2000
	s_nop 0
	global_load_lds_dwordx4 v[162:163], off
	v_lshl_add_u64 v[162:163], s[58:59], 0, v[132:133]
	s_mov_b32 m0, s15
	v_lshl_add_u64 v[202:203], v[162:163], 0, s[72:73]
	global_load_lds_dwordx4 v[162:163], off
	s_mov_b32 m0, s42
	s_nop 0
	global_load_lds_dwordx4 v[202:203], off
	s_waitcnt vmcnt(8)
	s_waitcnt lgkmcnt(0)
	s_barrier
	s_setprio 1
	s_waitcnt lgkmcnt(0)
	v_mfma_f32_16x16x32_bf16 v[62:65], v[138:141], v[198:201], 0
	v_mfma_f32_16x16x32_bf16 v[62:65], v[146:149], v[214:217], v[62:65]
	v_mfma_f32_16x16x32_bf16 v[58:61], v[150:153], v[198:201], 0
	v_mfma_f32_16x16x32_bf16 v[58:61], v[158:161], v[214:217], v[58:61]
	v_mfma_f32_16x16x32_bf16 v[46:49], v[138:141], v[218:221], 0
	v_mfma_f32_16x16x32_bf16 v[46:49], v[146:149], v[222:225], v[46:49]
	v_mfma_f32_16x16x32_bf16 v[42:45], v[150:153], v[218:221], 0
	v_mfma_f32_16x16x32_bf16 v[42:45], v[158:161], v[222:225], v[42:45]
	v_mfma_f32_16x16x32_bf16 v[30:33], v[138:141], v[226:229], 0
	v_mfma_f32_16x16x32_bf16 v[30:33], v[146:149], v[230:233], v[30:33]
	v_mfma_f32_16x16x32_bf16 v[26:29], v[150:153], v[226:229], 0
	v_mfma_f32_16x16x32_bf16 v[26:29], v[158:161], v[230:233], v[26:29]
	v_mfma_f32_16x16x32_bf16 v[14:17], v[138:141], v[234:237], 0
	v_mfma_f32_16x16x32_bf16 v[14:17], v[146:149], v[238:241], v[14:17]
	v_mfma_f32_16x16x32_bf16 v[10:13], v[150:153], v[234:237], 0
	v_mfma_f32_16x16x32_bf16 v[10:13], v[158:161], v[238:241], v[10:13]
	s_setprio 0
	s_setprio 1
	v_mfma_f32_16x16x32_bf16 v[54:57], v[182:185], v[198:201], 0
	v_mfma_f32_16x16x32_bf16 v[54:57], v[186:189], v[214:217], v[54:57]
	v_mfma_f32_16x16x32_bf16 v[50:53], v[190:193], v[198:201], 0
	v_mfma_f32_16x16x32_bf16 v[50:53], v[194:197], v[214:217], v[50:53]
	v_mfma_f32_16x16x32_bf16 v[38:41], v[182:185], v[218:221], 0
	v_mfma_f32_16x16x32_bf16 v[38:41], v[186:189], v[222:225], v[38:41]
	v_mfma_f32_16x16x32_bf16 v[34:37], v[190:193], v[218:221], 0
	v_mfma_f32_16x16x32_bf16 v[34:37], v[194:197], v[222:225], v[34:37]
	v_mfma_f32_16x16x32_bf16 v[22:25], v[182:185], v[226:229], 0
	v_mfma_f32_16x16x32_bf16 v[22:25], v[186:189], v[230:233], v[22:25]
	v_mfma_f32_16x16x32_bf16 v[18:21], v[190:193], v[226:229], 0
	v_mfma_f32_16x16x32_bf16 v[18:21], v[194:197], v[230:233], v[18:21]
	v_mfma_f32_16x16x32_bf16 v[6:9], v[182:185], v[234:237], 0
	v_mfma_f32_16x16x32_bf16 v[6:9], v[186:189], v[238:241], v[6:9]
	v_mfma_f32_16x16x32_bf16 v[2:5], v[190:193], v[234:237], 0
	v_mfma_f32_16x16x32_bf16 v[2:5], v[194:197], v[238:241], v[2:5]
	s_setprio 0
	s_barrier
	s_add_i32 s20, 0, 0x18000
	v_add_u32_e32 v0, s20, v145
	s_add_i32 s21, 0, 0x1c000
	ds_read_b128 v[138:141], v0
	ds_read_b128 v[146:149], v0 offset:1024
	ds_read_b128 v[150:153], v0 offset:2048
	ds_read_b128 v[158:161], v0 offset:3072
	v_add_u32_e32 v0, s21, v145
	ds_read_b128 v[182:185], v0
	ds_read_b128 v[186:189], v0 offset:1024
	ds_read_b128 v[190:193], v0 offset:2048
	ds_read_b128 v[194:197], v0 offset:3072
	ds_read_b128 v[198:201], v157 offset:32768
	ds_read_b128 v[214:217], v157 offset:33792
	ds_read_b128 v[218:221], v157 offset:34816
	ds_read_b128 v[222:225], v157 offset:35840
	ds_read_b128 v[226:229], v157 offset:36864
	ds_read_b128 v[230:233], v157 offset:37888
	ds_read_b128 v[234:237], v157 offset:38912
	ds_read_b128 v[238:241], v157 offset:39936
	s_mov_b32 m0, s43
	v_lshl_add_u64 v[202:203], v[162:163], 0, s[28:29]
	global_load_lds_dwordx4 v[202:203], off
	v_lshl_add_u64 v[202:203], v[162:163], 0, s[82:83]
	s_mov_b32 m0, s46
	s_nop 0
	global_load_lds_dwordx4 v[202:203], off
	s_waitcnt vmcnt(8)
	s_waitcnt lgkmcnt(0)
	s_barrier
	s_setprio 1
	s_waitcnt lgkmcnt(0)
	v_mfma_f32_16x16x32_bf16 v[126:129], v[138:141], v[198:201], v[126:129]
	v_mfma_f32_16x16x32_bf16 v[126:129], v[146:149], v[214:217], v[126:129]
	v_mfma_f32_16x16x32_bf16 v[122:125], v[150:153], v[198:201], v[122:125]
	v_mfma_f32_16x16x32_bf16 v[122:125], v[158:161], v[214:217], v[122:125]
	v_mfma_f32_16x16x32_bf16 v[110:113], v[138:141], v[218:221], v[110:113]
	v_mfma_f32_16x16x32_bf16 v[110:113], v[146:149], v[222:225], v[110:113]
	v_mfma_f32_16x16x32_bf16 v[106:109], v[150:153], v[218:221], v[106:109]
	v_mfma_f32_16x16x32_bf16 v[106:109], v[158:161], v[222:225], v[106:109]
	v_mfma_f32_16x16x32_bf16 v[94:97], v[138:141], v[226:229], v[94:97]
	v_mfma_f32_16x16x32_bf16 v[94:97], v[146:149], v[230:233], v[94:97]
	v_mfma_f32_16x16x32_bf16 v[90:93], v[150:153], v[226:229], v[90:93]
	v_mfma_f32_16x16x32_bf16 v[90:93], v[158:161], v[230:233], v[90:93]
	v_mfma_f32_16x16x32_bf16 v[78:81], v[138:141], v[234:237], v[78:81]
	v_mfma_f32_16x16x32_bf16 v[78:81], v[146:149], v[238:241], v[78:81]
	v_mfma_f32_16x16x32_bf16 v[74:77], v[150:153], v[234:237], v[74:77]
	v_mfma_f32_16x16x32_bf16 v[74:77], v[158:161], v[238:241], v[74:77]
	s_setprio 0
	s_setprio 1
	v_mfma_f32_16x16x32_bf16 v[118:121], v[182:185], v[198:201], v[118:121]
	v_mfma_f32_16x16x32_bf16 v[118:121], v[186:189], v[214:217], v[118:121]
	v_mfma_f32_16x16x32_bf16 v[114:117], v[190:193], v[198:201], v[114:117]
	v_mfma_f32_16x16x32_bf16 v[114:117], v[194:197], v[214:217], v[114:117]
	v_mfma_f32_16x16x32_bf16 v[102:105], v[182:185], v[218:221], v[102:105]
	v_mfma_f32_16x16x32_bf16 v[102:105], v[186:189], v[222:225], v[102:105]
	v_mfma_f32_16x16x32_bf16 v[98:101], v[190:193], v[218:221], v[98:101]
	v_mfma_f32_16x16x32_bf16 v[98:101], v[194:197], v[222:225], v[98:101]
	v_mfma_f32_16x16x32_bf16 v[86:89], v[182:185], v[226:229], v[86:89]
	v_mfma_f32_16x16x32_bf16 v[86:89], v[186:189], v[230:233], v[86:89]
	v_mfma_f32_16x16x32_bf16 v[82:85], v[190:193], v[226:229], v[82:85]
	v_mfma_f32_16x16x32_bf16 v[82:85], v[194:197], v[230:233], v[82:85]
	v_mfma_f32_16x16x32_bf16 v[70:73], v[182:185], v[234:237], v[70:73]
	v_mfma_f32_16x16x32_bf16 v[70:73], v[186:189], v[238:241], v[70:73]
	v_mfma_f32_16x16x32_bf16 v[66:69], v[190:193], v[234:237], v[66:69]
	v_mfma_f32_16x16x32_bf16 v[66:69], v[194:197], v[238:241], v[66:69]
	s_setprio 0
	s_barrier
	ds_read_b128 v[198:201], v157 offset:49152
	ds_read_b128 v[214:217], v157 offset:50176
	ds_read_b128 v[218:221], v157 offset:51200
	ds_read_b128 v[222:225], v157 offset:52224
	ds_read_b128 v[226:229], v157 offset:53248
	ds_read_b128 v[230:233], v157 offset:54272
	ds_read_b128 v[234:237], v157 offset:55296
	ds_read_b128 v[238:241], v157 offset:56320
	s_add_i32 s20, s20, s14
	v_lshl_add_u64 v[202:203], v[142:143], 0, s[34:35]
	s_mov_b32 m0, s20
	s_nop 0
	global_load_lds_dwordx4 v[202:203], off
	v_lshl_add_u64 v[202:203], v[142:143], 0, s[38:39]
	s_add_i32 m0, s20, 0x2000
	s_add_i32 s20, s21, s14
	global_load_lds_dwordx4 v[202:203], off
	v_lshl_add_u64 v[202:203], v[142:143], 0, s[44:45]
	s_mov_b32 m0, s20
	v_lshl_add_u64 v[142:143], v[142:143], 0, s[10:11]
	global_load_lds_dwordx4 v[202:203], off
	s_add_i32 m0, s20, 0x2000
	s_nop 0
	global_load_lds_dwordx4 v[142:143], off
	v_lshl_add_u64 v[142:143], v[162:163], 0, s[34:35]
	s_mov_b32 m0, s47
	s_nop 0
	global_load_lds_dwordx4 v[142:143], off
	v_lshl_add_u64 v[142:143], v[162:163], 0, s[38:39]
	s_mov_b32 m0, s96
	s_nop 0
	global_load_lds_dwordx4 v[142:143], off
	s_waitcnt vmcnt(8)
	s_waitcnt lgkmcnt(0)
	s_barrier
	s_setprio 1
	s_waitcnt lgkmcnt(0)
	v_mfma_f32_16x16x32_bf16 v[62:65], v[138:141], v[198:201], v[62:65]
	v_mfma_f32_16x16x32_bf16 v[62:65], v[146:149], v[214:217], v[62:65]
	v_mfma_f32_16x16x32_bf16 v[58:61], v[150:153], v[198:201], v[58:61]
	v_mfma_f32_16x16x32_bf16 v[58:61], v[158:161], v[214:217], v[58:61]
	v_mfma_f32_16x16x32_bf16 v[46:49], v[138:141], v[218:221], v[46:49]
	v_mfma_f32_16x16x32_bf16 v[46:49], v[146:149], v[222:225], v[46:49]
	v_mfma_f32_16x16x32_bf16 v[42:45], v[150:153], v[218:221], v[42:45]
	v_mfma_f32_16x16x32_bf16 v[42:45], v[158:161], v[222:225], v[42:45]
	v_mfma_f32_16x16x32_bf16 v[30:33], v[138:141], v[226:229], v[30:33]
	v_mfma_f32_16x16x32_bf16 v[30:33], v[146:149], v[230:233], v[30:33]
	v_mfma_f32_16x16x32_bf16 v[26:29], v[150:153], v[226:229], v[26:29]
	v_mfma_f32_16x16x32_bf16 v[26:29], v[158:161], v[230:233], v[26:29]
	v_mfma_f32_16x16x32_bf16 v[14:17], v[138:141], v[234:237], v[14:17]
	v_mfma_f32_16x16x32_bf16 v[14:17], v[146:149], v[238:241], v[14:17]
	v_mfma_f32_16x16x32_bf16 v[10:13], v[150:153], v[234:237], v[10:13]
	v_mfma_f32_16x16x32_bf16 v[10:13], v[158:161], v[238:241], v[10:13]
	s_add_i32 s91, s91, 2
	s_add_u32 s56, s56, 0x100
	s_addc_u32 s57, s57, 0
	s_add_u32 s86, s86, 0x100
	s_addc_u32 s87, s87, 0
	s_setprio 0
	s_setprio 1
	v_mfma_f32_16x16x32_bf16 v[54:57], v[182:185], v[198:201], v[54:57]
	v_mfma_f32_16x16x32_bf16 v[54:57], v[186:189], v[214:217], v[54:57]
	v_mfma_f32_16x16x32_bf16 v[50:53], v[190:193], v[198:201], v[50:53]
	v_mfma_f32_16x16x32_bf16 v[50:53], v[194:197], v[214:217], v[50:53]
	v_mfma_f32_16x16x32_bf16 v[38:41], v[182:185], v[218:221], v[38:41]
	v_mfma_f32_16x16x32_bf16 v[38:41], v[186:189], v[222:225], v[38:41]
	v_mfma_f32_16x16x32_bf16 v[34:37], v[190:193], v[218:221], v[34:37]
	v_mfma_f32_16x16x32_bf16 v[34:37], v[194:197], v[222:225], v[34:37]
	v_mfma_f32_16x16x32_bf16 v[22:25], v[182:185], v[226:229], v[22:25]
	v_mfma_f32_16x16x32_bf16 v[22:25], v[186:189], v[230:233], v[22:25]
	v_mfma_f32_16x16x32_bf16 v[18:21], v[190:193], v[226:229], v[18:21]
	v_mfma_f32_16x16x32_bf16 v[18:21], v[194:197], v[230:233], v[18:21]
	v_mfma_f32_16x16x32_bf16 v[6:9], v[182:185], v[234:237], v[6:9]
	v_mfma_f32_16x16x32_bf16 v[6:9], v[186:189], v[238:241], v[6:9]
	v_mfma_f32_16x16x32_bf16 v[2:5], v[190:193], v[234:237], v[2:5]
	v_mfma_f32_16x16x32_bf16 v[2:5], v[194:197], v[238:241], v[2:5]
	s_setprio 0
	s_barrier
	s_branch .LBB0_850
	.p2alignl 6, 3212836864
